# prompt conv: stats barrier skips the vmcnt(0) only in the first block (stage_tail DMA overlaps normalise), keeps it before the pool-mix staging
# speedup vs baseline: 1.0059x; 1.0059x over previous
; #define LAS __attribute__((address_space(3)))
; __device__ __forceinline__ float bf_lo(unsigned w) { return __uint_as_float(w << 16); }
; __device__ __forceinline__ float bf_hi(unsigned w) { return __uint_as_float(w & 0xffff0000u); }
; __device__ __forceinline__ void p2_conv_unit_prompt(Frame& F, int unit, int next_pm, const ConvW& cw, size_t src_off = WS_A, size_t dst_off = WS_CACT) {
;     ...
;         for (int rg = 0; rg < CV_ROWS; rg += 8) {
;             unsigned w2[8], w1[8];
; #pragma unroll
;             for (int i = 0; i < 8; ++i) if (rg + i < CV_ROWS) { const LAS unsigned char* rp = S + (rg + i) * (DCONV * 2) + ((rg + i) < CW - 1 ? ringLo : ringHi);
;                 w2[i] = *(const LAS unsigned*)(rp + p * 2u); w1[i] = *(const LAS unsigned short*)(rp + q * 2u); }
; #pragma unroll
;             for (int i = 0; i < 8; ++i) if (rg + i < CV_ROWS) { const int rr = rg + i; const f32x2 vp = (f32x2){bf_lo(w2[i]), bf_hi(w2[i])}; const float vq = bf_lo(w1[i]);
; #pragma unroll
;                 for (int t = 0; t < 16; ++t) { const int j = rr - t; if (j >= 0 && j < CW) { ap[t] += wp[j] * vp; aq[t] += wq[j] * vq; } } }
;             __builtin_amdgcn_sched_barrier(0); }
.LBB0_480:
	v_lshlrev_b32_e32 v1, 16, v145
	v_lshlrev_b32_e32 v38, 16, v36
	v_and_b32_e32 v39, 0xffff0000, v36
	v_pk_fma_f32 v[38:39], v[114:115], v[38:39], v[120:121]
	v_fma_f32 v145, v190, v1, v197
	v_lshlrev_b32_e32 v36, 16, v37
	v_and_b32_e32 v37, 0xffff0000, v37
	v_lshlrev_b32_e32 v1, 16, v144
	v_pk_fma_f32 v[38:39], v[116:117], v[36:37], v[38:39]
	v_fmac_f32_e32 v145, v191, v1
	v_pk_fma_f32 v[36:37], v[114:115], v[36:37], v[120:121]
	v_fma_f32 v144, v190, v1, v197
	v_lshlrev_b32_e32 v230, 16, v34
	v_and_b32_e32 v231, 0xffff0000, v34
	v_lshlrev_b32_e32 v1, 16, v143
	v_pk_fma_f32 v[38:39], v[118:119], v[230:231], v[38:39]
	v_fmac_f32_e32 v145, v192, v1
	v_pk_fma_f32 v[36:37], v[116:117], v[230:231], v[36:37]
	v_fmac_f32_e32 v144, v191, v1
	v_pk_fma_f32 v[230:231], v[114:115], v[230:231], v[120:121]
	v_fma_f32 v143, v190, v1, v197
	v_lshlrev_b32_e32 v34, 16, v35
	v_and_b32_e32 v35, 0xffff0000, v35
	v_lshlrev_b32_e32 v1, 16, v142
	v_pk_fma_f32 v[38:39], v[58:59], v[34:35], v[38:39]
	v_fmac_f32_e32 v145, v193, v1
	v_pk_fma_f32 v[36:37], v[118:119], v[34:35], v[36:37]
	v_fmac_f32_e32 v144, v192, v1
	v_pk_fma_f32 v[230:231], v[116:117], v[34:35], v[230:231]
	v_fmac_f32_e32 v143, v191, v1
	v_pk_fma_f32 v[34:35], v[114:115], v[34:35], v[120:121]
	v_fma_f32 v142, v190, v1, v197
	v_lshlrev_b32_e32 v232, 16, v32
	v_and_b32_e32 v233, 0xffff0000, v32
	v_lshlrev_b32_e32 v1, 16, v141
	v_pk_fma_f32 v[38:39], v[60:61], v[232:233], v[38:39]
	v_fmac_f32_e32 v145, v194, v1
	v_pk_fma_f32 v[36:37], v[58:59], v[232:233], v[36:37]
	v_fmac_f32_e32 v144, v193, v1
	v_pk_fma_f32 v[230:231], v[118:119], v[232:233], v[230:231]
	v_fmac_f32_e32 v143, v192, v1
	v_pk_fma_f32 v[34:35], v[116:117], v[232:233], v[34:35]
	v_fmac_f32_e32 v142, v191, v1
	v_pk_fma_f32 v[232:233], v[114:115], v[232:233], v[120:121]
	v_fma_f32 v141, v190, v1, v197
	v_lshlrev_b32_e32 v32, 16, v33
	v_and_b32_e32 v33, 0xffff0000, v33
	v_lshlrev_b32_e32 v1, 16, v140
	v_pk_fma_f32 v[38:39], v[62:63], v[32:33], v[38:39]
	v_fmac_f32_e32 v145, v195, v1
	v_pk_fma_f32 v[36:37], v[60:61], v[32:33], v[36:37]
	v_fmac_f32_e32 v144, v194, v1
	v_pk_fma_f32 v[230:231], v[58:59], v[32:33], v[230:231]
	v_fmac_f32_e32 v143, v193, v1
	v_pk_fma_f32 v[34:35], v[118:119], v[32:33], v[34:35]
	v_fmac_f32_e32 v142, v192, v1
	v_pk_fma_f32 v[232:233], v[116:117], v[32:33], v[232:233]
	v_fmac_f32_e32 v141, v191, v1
	v_pk_fma_f32 v[32:33], v[114:115], v[32:33], v[120:121]
	v_fma_f32 v140, v190, v1, v197
	v_lshlrev_b32_e32 v234, 16, v30
	v_and_b32_e32 v235, 0xffff0000, v30
	v_lshlrev_b32_e32 v1, 16, v139
	v_pk_fma_f32 v[38:39], v[64:65], v[234:235], v[38:39]
	v_fmac_f32_e32 v145, v196, v1
	v_pk_fma_f32 v[36:37], v[62:63], v[234:235], v[36:37]
	v_fmac_f32_e32 v144, v195, v1
	v_pk_fma_f32 v[230:231], v[60:61], v[234:235], v[230:231]
	v_fmac_f32_e32 v143, v194, v1
	v_pk_fma_f32 v[34:35], v[58:59], v[234:235], v[34:35]
	v_fmac_f32_e32 v142, v193, v1
	v_pk_fma_f32 v[232:233], v[118:119], v[234:235], v[232:233]
	v_fmac_f32_e32 v141, v192, v1
	v_pk_fma_f32 v[32:33], v[116:117], v[234:235], v[32:33]
	v_fmac_f32_e32 v140, v191, v1
	v_pk_fma_f32 v[234:235], v[114:115], v[234:235], v[120:121]
	v_fma_f32 v139, v190, v1, v197
	v_lshlrev_b32_e32 v30, 16, v31
	v_and_b32_e32 v31, 0xffff0000, v31
	v_lshlrev_b32_e32 v1, 16, v138
	v_pk_fma_f32 v[38:39], v[66:67], v[30:31], v[38:39]
	v_fmac_f32_e32 v145, v166, v1
	v_pk_fma_f32 v[36:37], v[64:65], v[30:31], v[36:37]
	v_fmac_f32_e32 v144, v196, v1
	v_pk_fma_f32 v[230:231], v[62:63], v[30:31], v[230:231]
	v_fmac_f32_e32 v143, v195, v1
	v_pk_fma_f32 v[34:35], v[60:61], v[30:31], v[34:35]
	v_fmac_f32_e32 v142, v194, v1
	v_pk_fma_f32 v[232:233], v[58:59], v[30:31], v[232:233]
	v_fmac_f32_e32 v141, v193, v1
	v_pk_fma_f32 v[32:33], v[118:119], v[30:31], v[32:33]
	v_fmac_f32_e32 v140, v192, v1
	v_pk_fma_f32 v[234:235], v[116:117], v[30:31], v[234:235]
	v_fmac_f32_e32 v139, v191, v1
	v_pk_fma_f32 v[30:31], v[114:115], v[30:31], v[120:121]
	v_fma_f32 v138, v190, v1, v197
	v_lshlrev_b32_e32 v236, 16, v28
	v_and_b32_e32 v237, 0xffff0000, v28
	v_lshlrev_b32_e32 v1, 16, v137
	v_pk_fma_f32 v[38:39], v[68:69], v[236:237], v[38:39]
	v_fmac_f32_e32 v145, v167, v1
	v_pk_fma_f32 v[36:37], v[66:67], v[236:237], v[36:37]
	v_fmac_f32_e32 v144, v166, v1
	v_pk_fma_f32 v[230:231], v[64:65], v[236:237], v[230:231]
	v_fmac_f32_e32 v143, v196, v1
	v_pk_fma_f32 v[34:35], v[62:63], v[236:237], v[34:35]
	v_fmac_f32_e32 v142, v195, v1
	v_pk_fma_f32 v[232:233], v[60:61], v[236:237], v[232:233]
	v_fmac_f32_e32 v141, v194, v1
	v_pk_fma_f32 v[32:33], v[58:59], v[236:237], v[32:33]
	v_fmac_f32_e32 v140, v193, v1
	v_pk_fma_f32 v[234:235], v[118:119], v[236:237], v[234:235]
	v_fmac_f32_e32 v139, v192, v1
	v_pk_fma_f32 v[30:31], v[116:117], v[236:237], v[30:31]
	v_fmac_f32_e32 v138, v191, v1
	v_pk_fma_f32 v[236:237], v[114:115], v[236:237], v[120:121]
	v_fma_f32 v137, v190, v1, v197
	v_lshlrev_b32_e32 v28, 16, v29
	v_and_b32_e32 v29, 0xffff0000, v29
	v_lshlrev_b32_e32 v1, 16, v136
	v_pk_fma_f32 v[38:39], v[70:71], v[28:29], v[38:39]
	v_fmac_f32_e32 v145, v168, v1
	v_pk_fma_f32 v[36:37], v[68:69], v[28:29], v[36:37]
	v_fmac_f32_e32 v144, v167, v1
	v_pk_fma_f32 v[230:231], v[66:67], v[28:29], v[230:231]
	v_fmac_f32_e32 v143, v166, v1
	v_pk_fma_f32 v[34:35], v[64:65], v[28:29], v[34:35]
	v_fmac_f32_e32 v142, v196, v1
	v_pk_fma_f32 v[232:233], v[62:63], v[28:29], v[232:233]
	v_fmac_f32_e32 v141, v195, v1
	v_pk_fma_f32 v[32:33], v[60:61], v[28:29], v[32:33]
	v_fmac_f32_e32 v140, v194, v1
	v_pk_fma_f32 v[234:235], v[58:59], v[28:29], v[234:235]
	v_fmac_f32_e32 v139, v193, v1
	v_pk_fma_f32 v[30:31], v[118:119], v[28:29], v[30:31]
; #define LAS __attribute__((address_space(3)))
; __device__ __forceinline__ float bf_lo(unsigned w) { return __uint_as_float(w << 16); }
; __device__ __forceinline__ float bf_hi(unsigned w) { return __uint_as_float(w & 0xffff0000u); }
; __device__ __forceinline__ void p2_conv_unit_prompt(Frame& F, int unit, int next_pm, const ConvW& cw, size_t src_off = WS_A, size_t dst_off = WS_CACT) {
;     ...
;         for (int rg = 0; rg < CV_ROWS; rg += 8) {
;             unsigned w2[8], w1[8];
; #pragma unroll
;             for (int i = 0; i < 8; ++i) if (rg + i < CV_ROWS) { const LAS unsigned char* rp = S + (rg + i) * (DCONV * 2) + ((rg + i) < CW - 1 ? ringLo : ringHi);
;                 w2[i] = *(const LAS unsigned*)(rp + p * 2u); w1[i] = *(const LAS unsigned short*)(rp + q * 2u); }
; #pragma unroll
;             for (int i = 0; i < 8; ++i) if (rg + i < CV_ROWS) { const int rr = rg + i; const f32x2 vp = (f32x2){bf_lo(w2[i]), bf_hi(w2[i])}; const float vq = bf_lo(w1[i]);
; #pragma unroll
;                 for (int t = 0; t < 16; ++t) { const int j = rr - t; if (j >= 0 && j < CW) { ap[t] += wp[j] * vp; aq[t] += wq[j] * vq; } } }
;             __builtin_amdgcn_sched_barrier(0); }
	v_fmac_f32_e32 v138, v192, v1
	v_pk_fma_f32 v[236:237], v[116:117], v[28:29], v[236:237]
	v_fmac_f32_e32 v137, v191, v1
	v_pk_fma_f32 v[28:29], v[114:115], v[28:29], v[120:121]
	v_fma_f32 v136, v190, v1, v197
	v_lshlrev_b32_e32 v238, 16, v26
	v_and_b32_e32 v239, 0xffff0000, v26
	v_lshlrev_b32_e32 v1, 16, v135
	v_pk_fma_f32 v[38:39], v[72:73], v[238:239], v[38:39]
	v_fmac_f32_e32 v145, v169, v1
	v_pk_fma_f32 v[36:37], v[70:71], v[238:239], v[36:37]
	v_fmac_f32_e32 v144, v168, v1
	v_pk_fma_f32 v[230:231], v[68:69], v[238:239], v[230:231]
	v_fmac_f32_e32 v143, v167, v1
	v_pk_fma_f32 v[34:35], v[66:67], v[238:239], v[34:35]
	v_fmac_f32_e32 v142, v166, v1
	v_pk_fma_f32 v[232:233], v[64:65], v[238:239], v[232:233]
	v_fmac_f32_e32 v141, v196, v1
	v_pk_fma_f32 v[32:33], v[62:63], v[238:239], v[32:33]
	v_fmac_f32_e32 v140, v195, v1
	v_pk_fma_f32 v[234:235], v[60:61], v[238:239], v[234:235]
	v_fmac_f32_e32 v139, v194, v1
	v_pk_fma_f32 v[30:31], v[58:59], v[238:239], v[30:31]
	v_fmac_f32_e32 v138, v193, v1
	v_pk_fma_f32 v[236:237], v[118:119], v[238:239], v[236:237]
	v_fmac_f32_e32 v137, v192, v1
	v_pk_fma_f32 v[28:29], v[116:117], v[238:239], v[28:29]
	v_fmac_f32_e32 v136, v191, v1
	v_pk_fma_f32 v[238:239], v[114:115], v[238:239], v[120:121]
	v_fma_f32 v135, v190, v1, v197
	v_lshlrev_b32_e32 v26, 16, v27
	v_and_b32_e32 v27, 0xffff0000, v27
	v_lshlrev_b32_e32 v1, 16, v134
	v_pk_fma_f32 v[38:39], v[74:75], v[26:27], v[38:39]
	v_fmac_f32_e32 v145, v170, v1
	v_pk_fma_f32 v[36:37], v[72:73], v[26:27], v[36:37]
	v_fmac_f32_e32 v144, v169, v1
	v_pk_fma_f32 v[230:231], v[70:71], v[26:27], v[230:231]
	v_fmac_f32_e32 v143, v168, v1
	v_pk_fma_f32 v[34:35], v[68:69], v[26:27], v[34:35]
	v_fmac_f32_e32 v142, v167, v1
	v_pk_fma_f32 v[232:233], v[66:67], v[26:27], v[232:233]
	v_fmac_f32_e32 v141, v166, v1
	v_pk_fma_f32 v[32:33], v[64:65], v[26:27], v[32:33]
	v_fmac_f32_e32 v140, v196, v1
	v_pk_fma_f32 v[234:235], v[62:63], v[26:27], v[234:235]
	v_fmac_f32_e32 v139, v195, v1
	v_pk_fma_f32 v[30:31], v[60:61], v[26:27], v[30:31]
	v_fmac_f32_e32 v138, v194, v1
	v_pk_fma_f32 v[236:237], v[58:59], v[26:27], v[236:237]
	v_fmac_f32_e32 v137, v193, v1
	v_pk_fma_f32 v[28:29], v[118:119], v[26:27], v[28:29]
	v_fmac_f32_e32 v136, v192, v1
	v_pk_fma_f32 v[238:239], v[116:117], v[26:27], v[238:239]
	v_fmac_f32_e32 v135, v191, v1
	v_pk_fma_f32 v[26:27], v[114:115], v[26:27], v[120:121]
	v_fma_f32 v134, v190, v1, v197
	v_lshlrev_b32_e32 v240, 16, v24
	v_and_b32_e32 v241, 0xffff0000, v24
	v_lshlrev_b32_e32 v1, 16, v133
	v_pk_fma_f32 v[38:39], v[76:77], v[240:241], v[38:39]
	v_fmac_f32_e32 v145, v171, v1
	v_pk_fma_f32 v[36:37], v[74:75], v[240:241], v[36:37]
	v_fmac_f32_e32 v144, v170, v1
	v_pk_fma_f32 v[230:231], v[72:73], v[240:241], v[230:231]
	v_fmac_f32_e32 v143, v169, v1
	v_pk_fma_f32 v[34:35], v[70:71], v[240:241], v[34:35]
	v_fmac_f32_e32 v142, v168, v1
	v_pk_fma_f32 v[232:233], v[68:69], v[240:241], v[232:233]
	v_fmac_f32_e32 v141, v167, v1
	v_pk_fma_f32 v[32:33], v[66:67], v[240:241], v[32:33]
	v_fmac_f32_e32 v140, v166, v1
	v_pk_fma_f32 v[234:235], v[64:65], v[240:241], v[234:235]
	v_fmac_f32_e32 v139, v196, v1
	v_pk_fma_f32 v[30:31], v[62:63], v[240:241], v[30:31]
	v_fmac_f32_e32 v138, v195, v1
	v_pk_fma_f32 v[236:237], v[60:61], v[240:241], v[236:237]
	v_fmac_f32_e32 v137, v194, v1
	v_pk_fma_f32 v[28:29], v[58:59], v[240:241], v[28:29]
	v_fmac_f32_e32 v136, v193, v1
	v_pk_fma_f32 v[238:239], v[118:119], v[240:241], v[238:239]
	v_fmac_f32_e32 v135, v192, v1
	v_pk_fma_f32 v[26:27], v[116:117], v[240:241], v[26:27]
	v_fmac_f32_e32 v134, v191, v1
	v_pk_fma_f32 v[240:241], v[114:115], v[240:241], v[120:121]
	v_fma_f32 v133, v190, v1, v197
	v_lshlrev_b32_e32 v24, 16, v25
	v_and_b32_e32 v25, 0xffff0000, v25
	v_lshlrev_b32_e32 v1, 16, v5
	v_pk_fma_f32 v[38:39], v[78:79], v[24:25], v[38:39]
	v_fmac_f32_e32 v145, v172, v1
	v_pk_fma_f32 v[36:37], v[76:77], v[24:25], v[36:37]
	v_fmac_f32_e32 v144, v171, v1
	v_pk_fma_f32 v[230:231], v[74:75], v[24:25], v[230:231]
	v_fmac_f32_e32 v143, v170, v1
	v_pk_fma_f32 v[34:35], v[72:73], v[24:25], v[34:35]
	v_fmac_f32_e32 v142, v169, v1
	v_pk_fma_f32 v[232:233], v[70:71], v[24:25], v[232:233]
	v_fmac_f32_e32 v141, v168, v1
	v_pk_fma_f32 v[32:33], v[68:69], v[24:25], v[32:33]
	v_fmac_f32_e32 v140, v167, v1
	v_pk_fma_f32 v[234:235], v[66:67], v[24:25], v[234:235]
	v_fmac_f32_e32 v139, v166, v1
	v_pk_fma_f32 v[30:31], v[64:65], v[24:25], v[30:31]
	v_fmac_f32_e32 v138, v196, v1
	v_pk_fma_f32 v[236:237], v[62:63], v[24:25], v[236:237]
	v_fmac_f32_e32 v137, v195, v1
	v_pk_fma_f32 v[28:29], v[60:61], v[24:25], v[28:29]
	v_fmac_f32_e32 v136, v194, v1
	v_pk_fma_f32 v[238:239], v[58:59], v[24:25], v[238:239]
	v_fmac_f32_e32 v135, v193, v1
	v_pk_fma_f32 v[26:27], v[118:119], v[24:25], v[26:27]
	v_fmac_f32_e32 v134, v192, v1
	v_pk_fma_f32 v[240:241], v[116:117], v[24:25], v[240:241]
	v_fmac_f32_e32 v133, v191, v1
	v_pk_fma_f32 v[24:25], v[114:115], v[24:25], v[120:121]
	v_fma_f32 v5, v190, v1, v197
	v_lshlrev_b32_e32 v242, 16, v22
	v_and_b32_e32 v243, 0xffff0000, v22
	v_lshlrev_b32_e32 v1, 16, v225
	v_pk_fma_f32 v[38:39], v[80:81], v[242:243], v[38:39]
	v_fmac_f32_e32 v145, v173, v1
	v_pk_fma_f32 v[36:37], v[78:79], v[242:243], v[36:37]
	v_fmac_f32_e32 v144, v172, v1
	v_pk_fma_f32 v[230:231], v[76:77], v[242:243], v[230:231]
	v_fmac_f32_e32 v143, v171, v1
	v_pk_fma_f32 v[34:35], v[74:75], v[242:243], v[34:35]
	v_fmac_f32_e32 v142, v170, v1
	v_pk_fma_f32 v[232:233], v[72:73], v[242:243], v[232:233]
	v_fmac_f32_e32 v141, v169, v1
	v_pk_fma_f32 v[32:33], v[70:71], v[242:243], v[32:33]
	v_fmac_f32_e32 v140, v168, v1
	v_pk_fma_f32 v[234:235], v[68:69], v[242:243], v[234:235]
; #define LAS __attribute__((address_space(3)))
; __device__ __forceinline__ float bf_lo(unsigned w) { return __uint_as_float(w << 16); }
; __device__ __forceinline__ float bf_hi(unsigned w) { return __uint_as_float(w & 0xffff0000u); }
; __device__ __forceinline__ void p2_conv_unit_prompt(Frame& F, int unit, int next_pm, const ConvW& cw, size_t src_off = WS_A, size_t dst_off = WS_CACT) {
;     ...
;         for (int rg = 0; rg < CV_ROWS; rg += 8) {
;             unsigned w2[8], w1[8];
; #pragma unroll
;             for (int i = 0; i < 8; ++i) if (rg + i < CV_ROWS) { const LAS unsigned char* rp = S + (rg + i) * (DCONV * 2) + ((rg + i) < CW - 1 ? ringLo : ringHi);
;                 w2[i] = *(const LAS unsigned*)(rp + p * 2u); w1[i] = *(const LAS unsigned short*)(rp + q * 2u); }
; #pragma unroll
;             for (int i = 0; i < 8; ++i) if (rg + i < CV_ROWS) { const int rr = rg + i; const f32x2 vp = (f32x2){bf_lo(w2[i]), bf_hi(w2[i])}; const float vq = bf_lo(w1[i]);
; #pragma unroll
;                 for (int t = 0; t < 16; ++t) { const int j = rr - t; if (j >= 0 && j < CW) { ap[t] += wp[j] * vp; aq[t] += wq[j] * vq; } } }
;             __builtin_amdgcn_sched_barrier(0); }
	v_fmac_f32_e32 v139, v167, v1
	v_pk_fma_f32 v[30:31], v[66:67], v[242:243], v[30:31]
	v_fmac_f32_e32 v138, v166, v1
	v_pk_fma_f32 v[236:237], v[64:65], v[242:243], v[236:237]
	v_fmac_f32_e32 v137, v196, v1
	v_pk_fma_f32 v[28:29], v[62:63], v[242:243], v[28:29]
	v_fmac_f32_e32 v136, v195, v1
	v_pk_fma_f32 v[238:239], v[60:61], v[242:243], v[238:239]
	v_fmac_f32_e32 v135, v194, v1
	v_pk_fma_f32 v[26:27], v[58:59], v[242:243], v[26:27]
	v_fmac_f32_e32 v134, v193, v1
	v_pk_fma_f32 v[240:241], v[118:119], v[242:243], v[240:241]
	v_fmac_f32_e32 v133, v192, v1
	v_pk_fma_f32 v[24:25], v[116:117], v[242:243], v[24:25]
	v_fmac_f32_e32 v5, v191, v1
	v_pk_fma_f32 v[242:243], v[114:115], v[242:243], v[120:121]
	v_fma_f32 v2, v190, v1, v197
	v_lshlrev_b32_e32 v22, 16, v23
	v_and_b32_e32 v23, 0xffff0000, v23
	v_lshlrev_b32_e32 v1, 16, v7
	v_pk_fma_f32 v[38:39], v[82:83], v[22:23], v[38:39]
	v_fmac_f32_e32 v145, v174, v1
	v_pk_fma_f32 v[36:37], v[80:81], v[22:23], v[36:37]
	v_fmac_f32_e32 v144, v173, v1
	v_pk_fma_f32 v[230:231], v[78:79], v[22:23], v[230:231]
	v_fmac_f32_e32 v143, v172, v1
	v_pk_fma_f32 v[34:35], v[76:77], v[22:23], v[34:35]
	v_fmac_f32_e32 v142, v171, v1
	v_pk_fma_f32 v[232:233], v[74:75], v[22:23], v[232:233]
	v_fmac_f32_e32 v141, v170, v1
	v_pk_fma_f32 v[32:33], v[72:73], v[22:23], v[32:33]
	v_fmac_f32_e32 v140, v169, v1
	v_pk_fma_f32 v[234:235], v[70:71], v[22:23], v[234:235]
	v_fmac_f32_e32 v139, v168, v1
	v_pk_fma_f32 v[30:31], v[68:69], v[22:23], v[30:31]
	v_fmac_f32_e32 v138, v167, v1
	v_pk_fma_f32 v[236:237], v[66:67], v[22:23], v[236:237]
	v_fmac_f32_e32 v137, v166, v1
	v_pk_fma_f32 v[28:29], v[64:65], v[22:23], v[28:29]
	v_fmac_f32_e32 v136, v196, v1
	v_pk_fma_f32 v[238:239], v[62:63], v[22:23], v[238:239]
	v_fmac_f32_e32 v135, v195, v1
	v_pk_fma_f32 v[26:27], v[60:61], v[22:23], v[26:27]
	v_fmac_f32_e32 v134, v194, v1
	v_pk_fma_f32 v[240:241], v[58:59], v[22:23], v[240:241]
	v_fmac_f32_e32 v133, v193, v1
	v_pk_fma_f32 v[24:25], v[118:119], v[22:23], v[24:25]
	v_fmac_f32_e32 v5, v192, v1
	v_pk_fma_f32 v[242:243], v[116:117], v[22:23], v[242:243]
	v_fmac_f32_e32 v2, v191, v1
	v_pk_fma_f32 v[22:23], v[114:115], v[22:23], v[120:121]
	v_fma_f32 v7, v190, v1, v197
	v_lshlrev_b32_e32 v244, 16, v20
	v_and_b32_e32 v245, 0xffff0000, v20
	v_lshlrev_b32_e32 v1, 16, v224
	v_pk_fma_f32 v[38:39], v[84:85], v[244:245], v[38:39]
	v_fmac_f32_e32 v145, v175, v1
	v_pk_fma_f32 v[36:37], v[82:83], v[244:245], v[36:37]
	v_fmac_f32_e32 v144, v174, v1
	v_pk_fma_f32 v[224:225], v[80:81], v[244:245], v[230:231]
	v_fmac_f32_e32 v143, v173, v1
	v_pk_fma_f32 v[34:35], v[78:79], v[244:245], v[34:35]
	v_fmac_f32_e32 v142, v172, v1
	v_pk_fma_f32 v[230:231], v[76:77], v[244:245], v[232:233]
	v_fmac_f32_e32 v141, v171, v1
	v_pk_fma_f32 v[32:33], v[74:75], v[244:245], v[32:33]
	v_fmac_f32_e32 v140, v170, v1
	v_pk_fma_f32 v[232:233], v[72:73], v[244:245], v[234:235]
	v_fmac_f32_e32 v139, v169, v1
	v_pk_fma_f32 v[30:31], v[70:71], v[244:245], v[30:31]
	v_fmac_f32_e32 v138, v168, v1
	v_pk_fma_f32 v[234:235], v[68:69], v[244:245], v[236:237]
	v_fmac_f32_e32 v137, v167, v1
	v_pk_fma_f32 v[28:29], v[66:67], v[244:245], v[28:29]
	v_fmac_f32_e32 v136, v166, v1
	v_pk_fma_f32 v[236:237], v[64:65], v[244:245], v[238:239]
	v_fmac_f32_e32 v135, v196, v1
	v_pk_fma_f32 v[26:27], v[62:63], v[244:245], v[26:27]
	v_fmac_f32_e32 v134, v195, v1
	v_pk_fma_f32 v[238:239], v[60:61], v[244:245], v[240:241]
	v_fmac_f32_e32 v133, v194, v1
	v_pk_fma_f32 v[24:25], v[58:59], v[244:245], v[24:25]
	v_fmac_f32_e32 v5, v193, v1
	v_pk_fma_f32 v[240:241], v[118:119], v[244:245], v[242:243]
	v_fmac_f32_e32 v2, v192, v1
	v_pk_fma_f32 v[22:23], v[116:117], v[244:245], v[22:23]
	v_fmac_f32_e32 v7, v191, v1
	v_lshlrev_b32_e32 v20, 16, v21
	v_and_b32_e32 v21, 0xffff0000, v21
	v_lshlrev_b32_e32 v1, 16, v223
	v_pk_fma_f32 v[38:39], v[86:87], v[20:21], v[38:39]
	v_fmac_f32_e32 v145, v176, v1
	v_pk_fma_f32 v[36:37], v[84:85], v[20:21], v[36:37]
	v_fmac_f32_e32 v144, v175, v1
	v_pk_fma_f32 v[224:225], v[82:83], v[20:21], v[224:225]
	v_fmac_f32_e32 v143, v174, v1
	v_pk_fma_f32 v[34:35], v[80:81], v[20:21], v[34:35]
	v_fmac_f32_e32 v142, v173, v1
	v_pk_fma_f32 v[230:231], v[78:79], v[20:21], v[230:231]
	v_fmac_f32_e32 v141, v172, v1
	v_pk_fma_f32 v[32:33], v[76:77], v[20:21], v[32:33]
	v_fmac_f32_e32 v140, v171, v1
	v_pk_fma_f32 v[232:233], v[74:75], v[20:21], v[232:233]
	v_fmac_f32_e32 v139, v170, v1
	v_pk_fma_f32 v[30:31], v[72:73], v[20:21], v[30:31]
	v_fmac_f32_e32 v138, v169, v1
	v_pk_fma_f32 v[234:235], v[70:71], v[20:21], v[234:235]
	v_fmac_f32_e32 v137, v168, v1
	v_pk_fma_f32 v[28:29], v[68:69], v[20:21], v[28:29]
	v_fmac_f32_e32 v136, v167, v1
	v_pk_fma_f32 v[236:237], v[66:67], v[20:21], v[236:237]
	v_fmac_f32_e32 v135, v166, v1
	v_pk_fma_f32 v[26:27], v[64:65], v[20:21], v[26:27]
	v_fmac_f32_e32 v134, v196, v1
	v_pk_fma_f32 v[238:239], v[62:63], v[20:21], v[238:239]
	v_fmac_f32_e32 v133, v195, v1
	v_pk_fma_f32 v[24:25], v[60:61], v[20:21], v[24:25]
	v_fmac_f32_e32 v5, v194, v1
	v_pk_fma_f32 v[240:241], v[58:59], v[20:21], v[240:241]
	v_fmac_f32_e32 v2, v193, v1
	v_pk_fma_f32 v[20:21], v[118:119], v[20:21], v[22:23]
	v_fmac_f32_e32 v7, v192, v1
	v_lshlrev_b32_e32 v22, 16, v18
	v_and_b32_e32 v23, 0xffff0000, v18
	v_lshlrev_b32_e32 v1, 16, v222
	v_pk_fma_f32 v[38:39], v[88:89], v[22:23], v[38:39]
	v_fmac_f32_e32 v145, v177, v1
	v_pk_fma_f32 v[36:37], v[86:87], v[22:23], v[36:37]
	v_fmac_f32_e32 v144, v176, v1
	v_pk_fma_f32 v[222:223], v[84:85], v[22:23], v[224:225]
	v_fmac_f32_e32 v143, v175, v1
	v_pk_fma_f32 v[34:35], v[82:83], v[22:23], v[34:35]
	v_fmac_f32_e32 v142, v174, v1
; #define LAS __attribute__((address_space(3)))
; __device__ __forceinline__ float bf_lo(unsigned w) { return __uint_as_float(w << 16); }
; __device__ __forceinline__ float bf_hi(unsigned w) { return __uint_as_float(w & 0xffff0000u); }
; __device__ __forceinline__ void p2_conv_unit_prompt(Frame& F, int unit, int next_pm, const ConvW& cw, size_t src_off = WS_A, size_t dst_off = WS_CACT) {
;     ...
;         for (int rg = 0; rg < CV_ROWS; rg += 8) {
;             unsigned w2[8], w1[8];
; #pragma unroll
;             for (int i = 0; i < 8; ++i) if (rg + i < CV_ROWS) { const LAS unsigned char* rp = S + (rg + i) * (DCONV * 2) + ((rg + i) < CW - 1 ? ringLo : ringHi);
;                 w2[i] = *(const LAS unsigned*)(rp + p * 2u); w1[i] = *(const LAS unsigned short*)(rp + q * 2u); }
; #pragma unroll
;             for (int i = 0; i < 8; ++i) if (rg + i < CV_ROWS) { const int rr = rg + i; const f32x2 vp = (f32x2){bf_lo(w2[i]), bf_hi(w2[i])}; const float vq = bf_lo(w1[i]);
; #pragma unroll
;                 for (int t = 0; t < 16; ++t) { const int j = rr - t; if (j >= 0 && j < CW) { ap[t] += wp[j] * vp; aq[t] += wq[j] * vq; } } }
;             __builtin_amdgcn_sched_barrier(0); }
	v_pk_fma_f32 v[224:225], v[80:81], v[22:23], v[230:231]
	v_fmac_f32_e32 v141, v173, v1
	v_pk_fma_f32 v[32:33], v[78:79], v[22:23], v[32:33]
	v_fmac_f32_e32 v140, v172, v1
	v_pk_fma_f32 v[230:231], v[76:77], v[22:23], v[232:233]
	v_fmac_f32_e32 v139, v171, v1
	v_pk_fma_f32 v[30:31], v[74:75], v[22:23], v[30:31]
	v_fmac_f32_e32 v138, v170, v1
	v_pk_fma_f32 v[232:233], v[72:73], v[22:23], v[234:235]
	v_fmac_f32_e32 v137, v169, v1
	v_pk_fma_f32 v[28:29], v[70:71], v[22:23], v[28:29]
	v_fmac_f32_e32 v136, v168, v1
	v_pk_fma_f32 v[234:235], v[68:69], v[22:23], v[236:237]
	v_fmac_f32_e32 v135, v167, v1
	v_pk_fma_f32 v[26:27], v[66:67], v[22:23], v[26:27]
	v_fmac_f32_e32 v134, v166, v1
	v_pk_fma_f32 v[236:237], v[64:65], v[22:23], v[238:239]
	v_fmac_f32_e32 v133, v196, v1
	v_pk_fma_f32 v[24:25], v[62:63], v[22:23], v[24:25]
	v_fmac_f32_e32 v5, v195, v1
	v_pk_fma_f32 v[238:239], v[60:61], v[22:23], v[240:241]
	v_fmac_f32_e32 v2, v194, v1
	v_pk_fma_f32 v[20:21], v[58:59], v[22:23], v[20:21]
	v_fmac_f32_e32 v7, v193, v1
	v_lshlrev_b32_e32 v18, 16, v19
	v_and_b32_e32 v19, 0xffff0000, v19
	v_lshlrev_b32_e32 v1, 16, v221
	v_pk_fma_f32 v[22:23], v[90:91], v[18:19], v[38:39]
	v_fmac_f32_e32 v145, v178, v1
	v_pk_fma_f32 v[36:37], v[88:89], v[18:19], v[36:37]
	v_fmac_f32_e32 v144, v177, v1
	v_pk_fma_f32 v[38:39], v[86:87], v[18:19], v[222:223]
	v_fmac_f32_e32 v143, v176, v1
	v_pk_fma_f32 v[34:35], v[84:85], v[18:19], v[34:35]
	v_fmac_f32_e32 v142, v175, v1
	v_pk_fma_f32 v[222:223], v[82:83], v[18:19], v[224:225]
	v_fmac_f32_e32 v141, v174, v1
	v_pk_fma_f32 v[32:33], v[80:81], v[18:19], v[32:33]
	v_fmac_f32_e32 v140, v173, v1
	v_pk_fma_f32 v[224:225], v[78:79], v[18:19], v[230:231]
	v_fmac_f32_e32 v139, v172, v1
	v_pk_fma_f32 v[30:31], v[76:77], v[18:19], v[30:31]
	v_fmac_f32_e32 v138, v171, v1
	v_pk_fma_f32 v[230:231], v[74:75], v[18:19], v[232:233]
	v_fmac_f32_e32 v137, v170, v1
	v_pk_fma_f32 v[28:29], v[72:73], v[18:19], v[28:29]
	v_fmac_f32_e32 v136, v169, v1
	v_pk_fma_f32 v[232:233], v[70:71], v[18:19], v[234:235]
	v_fmac_f32_e32 v135, v168, v1
	v_pk_fma_f32 v[26:27], v[68:69], v[18:19], v[26:27]
	v_fmac_f32_e32 v134, v167, v1
	v_pk_fma_f32 v[234:235], v[66:67], v[18:19], v[236:237]
	v_fmac_f32_e32 v133, v166, v1
	v_pk_fma_f32 v[24:25], v[64:65], v[18:19], v[24:25]
	v_fmac_f32_e32 v5, v196, v1
	v_pk_fma_f32 v[236:237], v[62:63], v[18:19], v[238:239]
	v_fmac_f32_e32 v2, v195, v1
	v_pk_fma_f32 v[18:19], v[60:61], v[18:19], v[20:21]
	v_fmac_f32_e32 v7, v194, v1
	v_lshlrev_b32_e32 v20, 16, v16
	v_and_b32_e32 v21, 0xffff0000, v16
	v_lshlrev_b32_e32 v1, 16, v220
	v_pk_fma_f32 v[22:23], v[92:93], v[20:21], v[22:23]
	v_fmac_f32_e32 v145, v179, v1
	v_pk_fma_f32 v[36:37], v[90:91], v[20:21], v[36:37]
	v_fmac_f32_e32 v144, v178, v1
	v_pk_fma_f32 v[38:39], v[88:89], v[20:21], v[38:39]
	v_fmac_f32_e32 v143, v177, v1
	v_pk_fma_f32 v[34:35], v[86:87], v[20:21], v[34:35]
	v_fmac_f32_e32 v142, v176, v1
	v_pk_fma_f32 v[220:221], v[84:85], v[20:21], v[222:223]
	v_fmac_f32_e32 v141, v175, v1
	v_pk_fma_f32 v[32:33], v[82:83], v[20:21], v[32:33]
	v_fmac_f32_e32 v140, v174, v1
	v_pk_fma_f32 v[222:223], v[80:81], v[20:21], v[224:225]
	v_fmac_f32_e32 v139, v173, v1
	v_pk_fma_f32 v[30:31], v[78:79], v[20:21], v[30:31]
	v_fmac_f32_e32 v138, v172, v1
	v_pk_fma_f32 v[224:225], v[76:77], v[20:21], v[230:231]
	v_fmac_f32_e32 v137, v171, v1
	v_pk_fma_f32 v[28:29], v[74:75], v[20:21], v[28:29]
	v_fmac_f32_e32 v136, v170, v1
	v_pk_fma_f32 v[230:231], v[72:73], v[20:21], v[232:233]
	v_fmac_f32_e32 v135, v169, v1
	v_pk_fma_f32 v[26:27], v[70:71], v[20:21], v[26:27]
	v_fmac_f32_e32 v134, v168, v1
	v_pk_fma_f32 v[232:233], v[68:69], v[20:21], v[234:235]
	v_fmac_f32_e32 v133, v167, v1
	v_pk_fma_f32 v[24:25], v[66:67], v[20:21], v[24:25]
	v_fmac_f32_e32 v5, v166, v1
	v_pk_fma_f32 v[234:235], v[64:65], v[20:21], v[236:237]
	v_fmac_f32_e32 v2, v196, v1
	v_pk_fma_f32 v[18:19], v[62:63], v[20:21], v[18:19]
	v_fmac_f32_e32 v7, v195, v1
	v_lshlrev_b32_e32 v16, 16, v17
	v_and_b32_e32 v17, 0xffff0000, v17
	v_lshlrev_b32_e32 v1, 16, v219
	v_pk_fma_f32 v[20:21], v[94:95], v[16:17], v[22:23]
	v_fmac_f32_e32 v145, v180, v1
	v_pk_fma_f32 v[22:23], v[92:93], v[16:17], v[36:37]
	v_fmac_f32_e32 v144, v179, v1
	v_pk_fma_f32 v[36:37], v[90:91], v[16:17], v[38:39]
	v_fmac_f32_e32 v143, v178, v1
	v_pk_fma_f32 v[34:35], v[88:89], v[16:17], v[34:35]
	v_fmac_f32_e32 v142, v177, v1
	v_pk_fma_f32 v[38:39], v[86:87], v[16:17], v[220:221]
	v_fmac_f32_e32 v141, v176, v1
	v_pk_fma_f32 v[32:33], v[84:85], v[16:17], v[32:33]
	v_fmac_f32_e32 v140, v175, v1
	v_pk_fma_f32 v[220:221], v[82:83], v[16:17], v[222:223]
	v_fmac_f32_e32 v139, v174, v1
	v_pk_fma_f32 v[30:31], v[80:81], v[16:17], v[30:31]
	v_fmac_f32_e32 v138, v173, v1
	v_pk_fma_f32 v[222:223], v[78:79], v[16:17], v[224:225]
	v_fmac_f32_e32 v137, v172, v1
	v_pk_fma_f32 v[28:29], v[76:77], v[16:17], v[28:29]
	v_fmac_f32_e32 v136, v171, v1
	v_pk_fma_f32 v[224:225], v[74:75], v[16:17], v[230:231]
	v_fmac_f32_e32 v135, v170, v1
	v_pk_fma_f32 v[26:27], v[72:73], v[16:17], v[26:27]
	v_fmac_f32_e32 v134, v169, v1
	v_pk_fma_f32 v[230:231], v[70:71], v[16:17], v[232:233]
	v_fmac_f32_e32 v133, v168, v1
	v_pk_fma_f32 v[24:25], v[68:69], v[16:17], v[24:25]
	v_fmac_f32_e32 v5, v167, v1
	v_pk_fma_f32 v[232:233], v[66:67], v[16:17], v[234:235]
	v_fmac_f32_e32 v2, v166, v1
	v_pk_fma_f32 v[16:17], v[64:65], v[16:17], v[18:19]
	v_fmac_f32_e32 v7, v196, v1
	v_lshlrev_b32_e32 v18, 16, v218
	v_and_b32_e32 v19, 0xffff0000, v218
	v_lshlrev_b32_e32 v1, 16, v217
	v_pk_fma_f32 v[20:21], v[96:97], v[18:19], v[20:21]
	v_fmac_f32_e32 v145, v181, v1
	v_pk_fma_f32 v[22:23], v[94:95], v[18:19], v[22:23]
; #define LAS __attribute__((address_space(3)))
; __device__ __forceinline__ float bf_lo(unsigned w) { return __uint_as_float(w << 16); }
; __device__ __forceinline__ float bf_hi(unsigned w) { return __uint_as_float(w & 0xffff0000u); }
; __device__ __forceinline__ void p2_conv_unit_prompt(Frame& F, int unit, int next_pm, const ConvW& cw, size_t src_off = WS_A, size_t dst_off = WS_CACT) {
;     ...
;         for (int rg = 0; rg < CV_ROWS; rg += 8) {
;             unsigned w2[8], w1[8];
; #pragma unroll
;             for (int i = 0; i < 8; ++i) if (rg + i < CV_ROWS) { const LAS unsigned char* rp = S + (rg + i) * (DCONV * 2) + ((rg + i) < CW - 1 ? ringLo : ringHi);
;                 w2[i] = *(const LAS unsigned*)(rp + p * 2u); w1[i] = *(const LAS unsigned short*)(rp + q * 2u); }
; #pragma unroll
;             for (int i = 0; i < 8; ++i) if (rg + i < CV_ROWS) { const int rr = rg + i; const f32x2 vp = (f32x2){bf_lo(w2[i]), bf_hi(w2[i])}; const float vq = bf_lo(w1[i]);
; #pragma unroll
;                 for (int t = 0; t < 16; ++t) { const int j = rr - t; if (j >= 0 && j < CW) { ap[t] += wp[j] * vp; aq[t] += wq[j] * vq; } } }
;             __builtin_amdgcn_sched_barrier(0); }
	v_fmac_f32_e32 v144, v180, v1
	v_pk_fma_f32 v[36:37], v[92:93], v[18:19], v[36:37]
	v_fmac_f32_e32 v143, v179, v1
	v_pk_fma_f32 v[34:35], v[90:91], v[18:19], v[34:35]
	v_fmac_f32_e32 v142, v178, v1
	v_pk_fma_f32 v[38:39], v[88:89], v[18:19], v[38:39]
	v_fmac_f32_e32 v141, v177, v1
	v_pk_fma_f32 v[32:33], v[86:87], v[18:19], v[32:33]
	v_fmac_f32_e32 v140, v176, v1
	v_pk_fma_f32 v[218:219], v[84:85], v[18:19], v[220:221]
	v_fmac_f32_e32 v139, v175, v1
	v_pk_fma_f32 v[30:31], v[82:83], v[18:19], v[30:31]
	v_fmac_f32_e32 v138, v174, v1
	v_pk_fma_f32 v[220:221], v[80:81], v[18:19], v[222:223]
	v_fmac_f32_e32 v137, v173, v1
	v_pk_fma_f32 v[28:29], v[78:79], v[18:19], v[28:29]
	v_fmac_f32_e32 v136, v172, v1
	v_pk_fma_f32 v[222:223], v[76:77], v[18:19], v[224:225]
	v_fmac_f32_e32 v135, v171, v1
	v_pk_fma_f32 v[26:27], v[74:75], v[18:19], v[26:27]
	v_fmac_f32_e32 v134, v170, v1
	v_pk_fma_f32 v[224:225], v[72:73], v[18:19], v[230:231]
	v_fmac_f32_e32 v133, v169, v1
	v_pk_fma_f32 v[24:25], v[70:71], v[18:19], v[24:25]
	v_fmac_f32_e32 v5, v168, v1
	v_pk_fma_f32 v[230:231], v[68:69], v[18:19], v[232:233]
	v_fmac_f32_e32 v2, v167, v1
	v_pk_fma_f32 v[16:17], v[66:67], v[18:19], v[16:17]
	v_fmac_f32_e32 v7, v166, v1
	v_lshlrev_b32_e32 v18, 16, v216
	v_and_b32_e32 v19, 0xffff0000, v216
	v_lshlrev_b32_e32 v1, 16, v215
	v_pk_fma_f32 v[20:21], v[98:99], v[18:19], v[20:21]
	v_fmac_f32_e32 v145, v182, v1
	v_pk_fma_f32 v[22:23], v[96:97], v[18:19], v[22:23]
	v_fmac_f32_e32 v144, v181, v1
	v_pk_fma_f32 v[36:37], v[94:95], v[18:19], v[36:37]
	v_fmac_f32_e32 v143, v180, v1
	v_pk_fma_f32 v[34:35], v[92:93], v[18:19], v[34:35]
	v_fmac_f32_e32 v142, v179, v1
	v_pk_fma_f32 v[38:39], v[90:91], v[18:19], v[38:39]
	v_fmac_f32_e32 v141, v178, v1
	v_pk_fma_f32 v[32:33], v[88:89], v[18:19], v[32:33]
	v_fmac_f32_e32 v140, v177, v1
	v_pk_fma_f32 v[214:215], v[86:87], v[18:19], v[218:219]
	v_fmac_f32_e32 v139, v176, v1
	v_pk_fma_f32 v[30:31], v[84:85], v[18:19], v[30:31]
	v_fmac_f32_e32 v138, v175, v1
	v_pk_fma_f32 v[216:217], v[82:83], v[18:19], v[220:221]
	v_fmac_f32_e32 v137, v174, v1
	v_pk_fma_f32 v[28:29], v[80:81], v[18:19], v[28:29]
	v_fmac_f32_e32 v136, v173, v1
	v_pk_fma_f32 v[218:219], v[78:79], v[18:19], v[222:223]
	v_fmac_f32_e32 v135, v172, v1
	v_pk_fma_f32 v[26:27], v[76:77], v[18:19], v[26:27]
	v_fmac_f32_e32 v134, v171, v1
	v_pk_fma_f32 v[220:221], v[74:75], v[18:19], v[224:225]
	v_fmac_f32_e32 v133, v170, v1
	v_pk_fma_f32 v[24:25], v[72:73], v[18:19], v[24:25]
	v_fmac_f32_e32 v5, v169, v1
	v_pk_fma_f32 v[222:223], v[70:71], v[18:19], v[230:231]
	v_fmac_f32_e32 v2, v168, v1
	v_pk_fma_f32 v[16:17], v[68:69], v[18:19], v[16:17]
	v_fmac_f32_e32 v7, v167, v1
	v_lshlrev_b32_e32 v18, 16, v213
	v_and_b32_e32 v19, 0xffff0000, v213
	v_lshlrev_b32_e32 v1, 16, v212
	v_pk_fma_f32 v[20:21], v[100:101], v[18:19], v[20:21]
	v_fmac_f32_e32 v145, v183, v1
	v_pk_fma_f32 v[22:23], v[98:99], v[18:19], v[22:23]
	v_fmac_f32_e32 v144, v182, v1
	v_pk_fma_f32 v[36:37], v[96:97], v[18:19], v[36:37]
	v_fmac_f32_e32 v143, v181, v1
	v_pk_fma_f32 v[34:35], v[94:95], v[18:19], v[34:35]
	v_fmac_f32_e32 v142, v180, v1
	v_pk_fma_f32 v[38:39], v[92:93], v[18:19], v[38:39]
	v_fmac_f32_e32 v141, v179, v1
	v_pk_fma_f32 v[32:33], v[90:91], v[18:19], v[32:33]
	v_fmac_f32_e32 v140, v178, v1
	v_pk_fma_f32 v[212:213], v[88:89], v[18:19], v[214:215]
	v_fmac_f32_e32 v139, v177, v1
	v_pk_fma_f32 v[30:31], v[86:87], v[18:19], v[30:31]
	v_fmac_f32_e32 v138, v176, v1
	v_pk_fma_f32 v[214:215], v[84:85], v[18:19], v[216:217]
	v_fmac_f32_e32 v137, v175, v1
	v_pk_fma_f32 v[28:29], v[82:83], v[18:19], v[28:29]
	v_fmac_f32_e32 v136, v174, v1
	v_pk_fma_f32 v[216:217], v[80:81], v[18:19], v[218:219]
	v_fmac_f32_e32 v135, v173, v1
	v_pk_fma_f32 v[26:27], v[78:79], v[18:19], v[26:27]
	v_fmac_f32_e32 v134, v172, v1
	v_pk_fma_f32 v[218:219], v[76:77], v[18:19], v[220:221]
	v_fmac_f32_e32 v133, v171, v1
	v_pk_fma_f32 v[24:25], v[74:75], v[18:19], v[24:25]
	v_fmac_f32_e32 v5, v170, v1
	v_pk_fma_f32 v[220:221], v[72:73], v[18:19], v[222:223]
	v_fmac_f32_e32 v2, v169, v1
	v_pk_fma_f32 v[16:17], v[70:71], v[18:19], v[16:17]
	v_fmac_f32_e32 v7, v168, v1
	v_lshlrev_b32_e32 v18, 16, v211
	v_and_b32_e32 v19, 0xffff0000, v211
	v_lshlrev_b32_e32 v1, 16, v210
	v_pk_fma_f32 v[20:21], v[102:103], v[18:19], v[20:21]
	v_fmac_f32_e32 v145, v184, v1
	v_pk_fma_f32 v[22:23], v[100:101], v[18:19], v[22:23]
	v_fmac_f32_e32 v144, v183, v1
	v_pk_fma_f32 v[36:37], v[98:99], v[18:19], v[36:37]
	v_fmac_f32_e32 v143, v182, v1
	v_pk_fma_f32 v[34:35], v[96:97], v[18:19], v[34:35]
	v_fmac_f32_e32 v142, v181, v1
	v_pk_fma_f32 v[38:39], v[94:95], v[18:19], v[38:39]
	v_fmac_f32_e32 v141, v180, v1
	v_pk_fma_f32 v[32:33], v[92:93], v[18:19], v[32:33]
	v_fmac_f32_e32 v140, v179, v1
	v_pk_fma_f32 v[210:211], v[90:91], v[18:19], v[212:213]
	v_fmac_f32_e32 v139, v178, v1
	v_pk_fma_f32 v[30:31], v[88:89], v[18:19], v[30:31]
	v_fmac_f32_e32 v138, v177, v1
	v_pk_fma_f32 v[212:213], v[86:87], v[18:19], v[214:215]
	v_fmac_f32_e32 v137, v176, v1
	v_pk_fma_f32 v[28:29], v[84:85], v[18:19], v[28:29]
	v_fmac_f32_e32 v136, v175, v1
	v_pk_fma_f32 v[214:215], v[82:83], v[18:19], v[216:217]
	v_fmac_f32_e32 v135, v174, v1
	v_pk_fma_f32 v[26:27], v[80:81], v[18:19], v[26:27]
	v_fmac_f32_e32 v134, v173, v1
	v_pk_fma_f32 v[216:217], v[78:79], v[18:19], v[218:219]
	v_fmac_f32_e32 v133, v172, v1
	v_pk_fma_f32 v[24:25], v[76:77], v[18:19], v[24:25]
	v_fmac_f32_e32 v5, v171, v1
	v_pk_fma_f32 v[218:219], v[74:75], v[18:19], v[220:221]
	v_fmac_f32_e32 v2, v170, v1
	v_pk_fma_f32 v[16:17], v[72:73], v[18:19], v[16:17]
	v_fmac_f32_e32 v7, v169, v1
	v_lshlrev_b32_e32 v18, 16, v209
; #define LAS __attribute__((address_space(3)))
; __device__ __forceinline__ float bf_lo(unsigned w) { return __uint_as_float(w << 16); }
; __device__ __forceinline__ float bf_hi(unsigned w) { return __uint_as_float(w & 0xffff0000u); }
; __device__ __forceinline__ void p2_conv_unit_prompt(Frame& F, int unit, int next_pm, const ConvW& cw, size_t src_off = WS_A, size_t dst_off = WS_CACT) {
;     ...
;         for (int rg = 0; rg < CV_ROWS; rg += 8) {
;             unsigned w2[8], w1[8];
; #pragma unroll
;             for (int i = 0; i < 8; ++i) if (rg + i < CV_ROWS) { const LAS unsigned char* rp = S + (rg + i) * (DCONV * 2) + ((rg + i) < CW - 1 ? ringLo : ringHi);
;                 w2[i] = *(const LAS unsigned*)(rp + p * 2u); w1[i] = *(const LAS unsigned short*)(rp + q * 2u); }
; #pragma unroll
;             for (int i = 0; i < 8; ++i) if (rg + i < CV_ROWS) { const int rr = rg + i; const f32x2 vp = (f32x2){bf_lo(w2[i]), bf_hi(w2[i])}; const float vq = bf_lo(w1[i]);
; #pragma unroll
;                 for (int t = 0; t < 16; ++t) { const int j = rr - t; if (j >= 0 && j < CW) { ap[t] += wp[j] * vp; aq[t] += wq[j] * vq; } } }
;             __builtin_amdgcn_sched_barrier(0); }
	v_and_b32_e32 v19, 0xffff0000, v209
	v_lshlrev_b32_e32 v1, 16, v208
	v_pk_fma_f32 v[20:21], v[104:105], v[18:19], v[20:21]
	v_fmac_f32_e32 v145, v185, v1
	v_pk_fma_f32 v[22:23], v[102:103], v[18:19], v[22:23]
	v_fmac_f32_e32 v144, v184, v1
	v_pk_fma_f32 v[36:37], v[100:101], v[18:19], v[36:37]
	v_fmac_f32_e32 v143, v183, v1
	v_pk_fma_f32 v[34:35], v[98:99], v[18:19], v[34:35]
	v_fmac_f32_e32 v142, v182, v1
	v_pk_fma_f32 v[38:39], v[96:97], v[18:19], v[38:39]
	v_fmac_f32_e32 v141, v181, v1
	v_pk_fma_f32 v[32:33], v[94:95], v[18:19], v[32:33]
	v_fmac_f32_e32 v140, v180, v1
	v_pk_fma_f32 v[208:209], v[92:93], v[18:19], v[210:211]
	v_fmac_f32_e32 v139, v179, v1
	v_pk_fma_f32 v[30:31], v[90:91], v[18:19], v[30:31]
	v_fmac_f32_e32 v138, v178, v1
	v_pk_fma_f32 v[210:211], v[88:89], v[18:19], v[212:213]
	v_fmac_f32_e32 v137, v177, v1
	v_pk_fma_f32 v[28:29], v[86:87], v[18:19], v[28:29]
	v_fmac_f32_e32 v136, v176, v1
	v_pk_fma_f32 v[212:213], v[84:85], v[18:19], v[214:215]
	v_fmac_f32_e32 v135, v175, v1
	v_pk_fma_f32 v[26:27], v[82:83], v[18:19], v[26:27]
	v_fmac_f32_e32 v134, v174, v1
	v_pk_fma_f32 v[214:215], v[80:81], v[18:19], v[216:217]
	v_fmac_f32_e32 v133, v173, v1
	v_pk_fma_f32 v[24:25], v[78:79], v[18:19], v[24:25]
	v_fmac_f32_e32 v5, v172, v1
	v_pk_fma_f32 v[216:217], v[76:77], v[18:19], v[218:219]
	v_fmac_f32_e32 v2, v171, v1
	v_pk_fma_f32 v[16:17], v[74:75], v[18:19], v[16:17]
	v_fmac_f32_e32 v7, v170, v1
	v_lshlrev_b32_e32 v18, 16, v207
	v_and_b32_e32 v19, 0xffff0000, v207
	v_lshlrev_b32_e32 v1, 16, v206
	v_pk_fma_f32 v[20:21], v[106:107], v[18:19], v[20:21]
	v_fmac_f32_e32 v145, v186, v1
	v_pk_fma_f32 v[22:23], v[104:105], v[18:19], v[22:23]
	v_fmac_f32_e32 v144, v185, v1
	v_pk_fma_f32 v[36:37], v[102:103], v[18:19], v[36:37]
	v_fmac_f32_e32 v143, v184, v1
	v_pk_fma_f32 v[34:35], v[100:101], v[18:19], v[34:35]
	v_fmac_f32_e32 v142, v183, v1
	v_pk_fma_f32 v[38:39], v[98:99], v[18:19], v[38:39]
	v_fmac_f32_e32 v141, v182, v1
	v_pk_fma_f32 v[32:33], v[96:97], v[18:19], v[32:33]
	v_fmac_f32_e32 v140, v181, v1
	v_pk_fma_f32 v[206:207], v[94:95], v[18:19], v[208:209]
	v_fmac_f32_e32 v139, v180, v1
	v_pk_fma_f32 v[30:31], v[92:93], v[18:19], v[30:31]
	v_fmac_f32_e32 v138, v179, v1
	v_pk_fma_f32 v[208:209], v[90:91], v[18:19], v[210:211]
	v_fmac_f32_e32 v137, v178, v1
	v_pk_fma_f32 v[28:29], v[88:89], v[18:19], v[28:29]
	v_fmac_f32_e32 v136, v177, v1
	v_pk_fma_f32 v[210:211], v[86:87], v[18:19], v[212:213]
	v_fmac_f32_e32 v135, v176, v1
	v_pk_fma_f32 v[26:27], v[84:85], v[18:19], v[26:27]
	v_fmac_f32_e32 v134, v175, v1
	v_pk_fma_f32 v[212:213], v[82:83], v[18:19], v[214:215]
	v_fmac_f32_e32 v133, v174, v1
	v_pk_fma_f32 v[24:25], v[80:81], v[18:19], v[24:25]
	v_fmac_f32_e32 v5, v173, v1
	v_pk_fma_f32 v[214:215], v[78:79], v[18:19], v[216:217]
	v_fmac_f32_e32 v2, v172, v1
	v_pk_fma_f32 v[16:17], v[76:77], v[18:19], v[16:17]
	v_fmac_f32_e32 v7, v171, v1
	v_lshlrev_b32_e32 v18, 16, v205
	v_and_b32_e32 v19, 0xffff0000, v205
	v_lshlrev_b32_e32 v1, 16, v204
	v_pk_fma_f32 v[20:21], v[108:109], v[18:19], v[20:21]
	v_fmac_f32_e32 v145, v187, v1
	v_pk_fma_f32 v[22:23], v[106:107], v[18:19], v[22:23]
	v_fmac_f32_e32 v144, v186, v1
	v_pk_fma_f32 v[36:37], v[104:105], v[18:19], v[36:37]
	v_fmac_f32_e32 v143, v185, v1
	v_pk_fma_f32 v[34:35], v[102:103], v[18:19], v[34:35]
	v_fmac_f32_e32 v142, v184, v1
	v_pk_fma_f32 v[38:39], v[100:101], v[18:19], v[38:39]
	v_fmac_f32_e32 v141, v183, v1
	v_pk_fma_f32 v[32:33], v[98:99], v[18:19], v[32:33]
	v_fmac_f32_e32 v140, v182, v1
	v_pk_fma_f32 v[204:205], v[96:97], v[18:19], v[206:207]
	v_fmac_f32_e32 v139, v181, v1
	v_pk_fma_f32 v[30:31], v[94:95], v[18:19], v[30:31]
	v_fmac_f32_e32 v138, v180, v1
	v_pk_fma_f32 v[206:207], v[92:93], v[18:19], v[208:209]
	v_fmac_f32_e32 v137, v179, v1
	v_pk_fma_f32 v[28:29], v[90:91], v[18:19], v[28:29]
	v_fmac_f32_e32 v136, v178, v1
	v_pk_fma_f32 v[208:209], v[88:89], v[18:19], v[210:211]
	v_fmac_f32_e32 v135, v177, v1
	v_pk_fma_f32 v[26:27], v[86:87], v[18:19], v[26:27]
	v_fmac_f32_e32 v134, v176, v1
	v_pk_fma_f32 v[210:211], v[84:85], v[18:19], v[212:213]
	v_fmac_f32_e32 v133, v175, v1
	v_pk_fma_f32 v[24:25], v[82:83], v[18:19], v[24:25]
	v_fmac_f32_e32 v5, v174, v1
	v_pk_fma_f32 v[212:213], v[80:81], v[18:19], v[214:215]
	v_fmac_f32_e32 v2, v173, v1
	v_pk_fma_f32 v[16:17], v[78:79], v[18:19], v[16:17]
	v_fmac_f32_e32 v7, v172, v1
	v_lshlrev_b32_e32 v18, 16, v203
	v_and_b32_e32 v19, 0xffff0000, v203
	v_lshlrev_b32_e32 v1, 16, v202
	v_pk_fma_f32 v[20:21], v[110:111], v[18:19], v[20:21]
	v_fmac_f32_e32 v145, v188, v1
	v_pk_fma_f32 v[22:23], v[108:109], v[18:19], v[22:23]
	v_fmac_f32_e32 v144, v187, v1
	v_pk_fma_f32 v[36:37], v[106:107], v[18:19], v[36:37]
	v_fmac_f32_e32 v143, v186, v1
	v_pk_fma_f32 v[34:35], v[104:105], v[18:19], v[34:35]
	v_fmac_f32_e32 v142, v185, v1
	v_pk_fma_f32 v[38:39], v[102:103], v[18:19], v[38:39]
	v_fmac_f32_e32 v141, v184, v1
	v_pk_fma_f32 v[32:33], v[100:101], v[18:19], v[32:33]
	v_fmac_f32_e32 v140, v183, v1
	v_pk_fma_f32 v[202:203], v[98:99], v[18:19], v[204:205]
	v_fmac_f32_e32 v139, v182, v1
	v_pk_fma_f32 v[30:31], v[96:97], v[18:19], v[30:31]
	v_fmac_f32_e32 v138, v181, v1
	v_pk_fma_f32 v[204:205], v[94:95], v[18:19], v[206:207]
	v_fmac_f32_e32 v137, v180, v1
	v_pk_fma_f32 v[28:29], v[92:93], v[18:19], v[28:29]
	v_fmac_f32_e32 v136, v179, v1
	v_pk_fma_f32 v[206:207], v[90:91], v[18:19], v[208:209]
	v_fmac_f32_e32 v135, v178, v1
	v_pk_fma_f32 v[26:27], v[88:89], v[18:19], v[26:27]
	v_fmac_f32_e32 v134, v177, v1
	v_pk_fma_f32 v[208:209], v[86:87], v[18:19], v[210:211]
	v_fmac_f32_e32 v133, v176, v1
	v_pk_fma_f32 v[24:25], v[84:85], v[18:19], v[24:25]
; #define LAS __attribute__((address_space(3)))
; __device__ __forceinline__ float bf_lo(unsigned w) { return __uint_as_float(w << 16); }
; __device__ __forceinline__ float bf_hi(unsigned w) { return __uint_as_float(w & 0xffff0000u); }
; __device__ __forceinline__ void p2_conv_unit_prompt(Frame& F, int unit, int next_pm, const ConvW& cw, size_t src_off = WS_A, size_t dst_off = WS_CACT) {
;     ...
;         for (int rg = 0; rg < CV_ROWS; rg += 8) {
;             unsigned w2[8], w1[8];
; #pragma unroll
;             for (int i = 0; i < 8; ++i) if (rg + i < CV_ROWS) { const LAS unsigned char* rp = S + (rg + i) * (DCONV * 2) + ((rg + i) < CW - 1 ? ringLo : ringHi);
;                 w2[i] = *(const LAS unsigned*)(rp + p * 2u); w1[i] = *(const LAS unsigned short*)(rp + q * 2u); }
; #pragma unroll
;             for (int i = 0; i < 8; ++i) if (rg + i < CV_ROWS) { const int rr = rg + i; const f32x2 vp = (f32x2){bf_lo(w2[i]), bf_hi(w2[i])}; const float vq = bf_lo(w1[i]);
; #pragma unroll
;                 for (int t = 0; t < 16; ++t) { const int j = rr - t; if (j >= 0 && j < CW) { ap[t] += wp[j] * vp; aq[t] += wq[j] * vq; } } }
;             __builtin_amdgcn_sched_barrier(0); }
	v_fmac_f32_e32 v5, v175, v1
	v_pk_fma_f32 v[210:211], v[82:83], v[18:19], v[212:213]
	v_fmac_f32_e32 v2, v174, v1
	v_pk_fma_f32 v[16:17], v[80:81], v[18:19], v[16:17]
	v_fmac_f32_e32 v7, v173, v1
	v_lshlrev_b32_e32 v18, 16, v41
	v_and_b32_e32 v19, 0xffff0000, v41
	v_lshlrev_b32_e32 v1, 16, v40
	v_pk_fma_f32 v[40:41], v[112:113], v[18:19], v[20:21]
	v_fmac_f32_e32 v145, v189, v1
	v_pk_fma_f32 v[20:21], v[110:111], v[18:19], v[22:23]
	v_fmac_f32_e32 v144, v188, v1
	v_pk_fma_f32 v[22:23], v[108:109], v[18:19], v[36:37]
	v_fmac_f32_e32 v143, v187, v1
	v_pk_fma_f32 v[34:35], v[106:107], v[18:19], v[34:35]
	v_fmac_f32_e32 v142, v186, v1
	v_pk_fma_f32 v[36:37], v[104:105], v[18:19], v[38:39]
	v_fmac_f32_e32 v141, v185, v1
	v_pk_fma_f32 v[32:33], v[102:103], v[18:19], v[32:33]
	v_fmac_f32_e32 v140, v184, v1
	v_pk_fma_f32 v[38:39], v[100:101], v[18:19], v[202:203]
	v_fmac_f32_e32 v139, v183, v1
	v_pk_fma_f32 v[30:31], v[98:99], v[18:19], v[30:31]
	v_fmac_f32_e32 v138, v182, v1
	v_pk_fma_f32 v[202:203], v[96:97], v[18:19], v[204:205]
	v_fmac_f32_e32 v137, v181, v1
	v_pk_fma_f32 v[28:29], v[94:95], v[18:19], v[28:29]
	v_fmac_f32_e32 v136, v180, v1
	v_pk_fma_f32 v[204:205], v[92:93], v[18:19], v[206:207]
	v_fmac_f32_e32 v135, v179, v1
	v_pk_fma_f32 v[26:27], v[90:91], v[18:19], v[26:27]
	v_fmac_f32_e32 v134, v178, v1
	v_pk_fma_f32 v[206:207], v[88:89], v[18:19], v[208:209]
	v_fmac_f32_e32 v133, v177, v1
	v_pk_fma_f32 v[24:25], v[86:87], v[18:19], v[24:25]
	v_fmac_f32_e32 v5, v176, v1
	v_pk_fma_f32 v[208:209], v[84:85], v[18:19], v[210:211]
	v_fmac_f32_e32 v2, v175, v1
	v_pk_fma_f32 v[16:17], v[82:83], v[18:19], v[16:17]
	v_fmac_f32_e32 v7, v174, v1
	v_lshlrev_b32_e32 v18, 16, v47
	v_and_b32_e32 v19, 0xffff0000, v47
	v_lshlrev_b32_e32 v1, 16, v46
	v_pk_fma_f32 v[46:47], v[112:113], v[18:19], v[20:21]
	v_fmac_f32_e32 v144, v189, v1
	v_pk_fma_f32 v[20:21], v[110:111], v[18:19], v[22:23]
	v_fmac_f32_e32 v143, v188, v1
	v_pk_fma_f32 v[22:23], v[108:109], v[18:19], v[34:35]
	v_fmac_f32_e32 v142, v187, v1
	v_pk_fma_f32 v[34:35], v[106:107], v[18:19], v[36:37]
	v_fmac_f32_e32 v141, v186, v1
	v_pk_fma_f32 v[32:33], v[104:105], v[18:19], v[32:33]
	v_fmac_f32_e32 v140, v185, v1
	v_pk_fma_f32 v[36:37], v[102:103], v[18:19], v[38:39]
	v_fmac_f32_e32 v139, v184, v1
	v_pk_fma_f32 v[30:31], v[100:101], v[18:19], v[30:31]
	v_fmac_f32_e32 v138, v183, v1
	v_pk_fma_f32 v[38:39], v[98:99], v[18:19], v[202:203]
	v_fmac_f32_e32 v137, v182, v1
	v_pk_fma_f32 v[28:29], v[96:97], v[18:19], v[28:29]
	v_fmac_f32_e32 v136, v181, v1
	v_pk_fma_f32 v[202:203], v[94:95], v[18:19], v[204:205]
	v_fmac_f32_e32 v135, v180, v1
	v_pk_fma_f32 v[26:27], v[92:93], v[18:19], v[26:27]
	v_fmac_f32_e32 v134, v179, v1
	v_pk_fma_f32 v[204:205], v[90:91], v[18:19], v[206:207]
	v_fmac_f32_e32 v133, v178, v1
	v_pk_fma_f32 v[24:25], v[88:89], v[18:19], v[24:25]
	v_fmac_f32_e32 v5, v177, v1
	v_pk_fma_f32 v[206:207], v[86:87], v[18:19], v[208:209]
	v_fmac_f32_e32 v2, v176, v1
	v_pk_fma_f32 v[16:17], v[84:85], v[18:19], v[16:17]
	v_fmac_f32_e32 v7, v175, v1
	v_lshlrev_b32_e32 v18, 16, v45
	v_and_b32_e32 v19, 0xffff0000, v45
	v_lshlrev_b32_e32 v1, 16, v44
	v_pk_fma_f32 v[44:45], v[112:113], v[18:19], v[20:21]
	v_fmac_f32_e32 v143, v189, v1
	v_pk_fma_f32 v[20:21], v[110:111], v[18:19], v[22:23]
	v_fmac_f32_e32 v142, v188, v1
	v_pk_fma_f32 v[22:23], v[108:109], v[18:19], v[34:35]
	v_fmac_f32_e32 v141, v187, v1
	v_pk_fma_f32 v[32:33], v[106:107], v[18:19], v[32:33]
	v_fmac_f32_e32 v140, v186, v1
	v_pk_fma_f32 v[34:35], v[104:105], v[18:19], v[36:37]
	v_fmac_f32_e32 v139, v185, v1
	v_pk_fma_f32 v[30:31], v[102:103], v[18:19], v[30:31]
	v_fmac_f32_e32 v138, v184, v1
	v_pk_fma_f32 v[36:37], v[100:101], v[18:19], v[38:39]
	v_fmac_f32_e32 v137, v183, v1
	v_pk_fma_f32 v[28:29], v[98:99], v[18:19], v[28:29]
	v_fmac_f32_e32 v136, v182, v1
	v_pk_fma_f32 v[38:39], v[96:97], v[18:19], v[202:203]
	v_fmac_f32_e32 v135, v181, v1
	v_pk_fma_f32 v[26:27], v[94:95], v[18:19], v[26:27]
	v_fmac_f32_e32 v134, v180, v1
	v_pk_fma_f32 v[202:203], v[92:93], v[18:19], v[204:205]
	v_fmac_f32_e32 v133, v179, v1
	v_pk_fma_f32 v[24:25], v[90:91], v[18:19], v[24:25]
	v_fmac_f32_e32 v5, v178, v1
	v_pk_fma_f32 v[204:205], v[88:89], v[18:19], v[206:207]
	v_fmac_f32_e32 v2, v177, v1
	v_pk_fma_f32 v[16:17], v[86:87], v[18:19], v[16:17]
	v_fmac_f32_e32 v7, v176, v1
	v_lshlrev_b32_e32 v18, 16, v43
	v_and_b32_e32 v19, 0xffff0000, v43
	v_lshlrev_b32_e32 v1, 16, v42
	v_pk_fma_f32 v[42:43], v[112:113], v[18:19], v[20:21]
	v_fmac_f32_e32 v142, v189, v1
	v_pk_fma_f32 v[20:21], v[110:111], v[18:19], v[22:23]
	v_fmac_f32_e32 v141, v188, v1
	v_pk_fma_f32 v[22:23], v[108:109], v[18:19], v[32:33]
	v_fmac_f32_e32 v140, v187, v1
	v_pk_fma_f32 v[32:33], v[106:107], v[18:19], v[34:35]
	v_fmac_f32_e32 v139, v186, v1
	v_pk_fma_f32 v[30:31], v[104:105], v[18:19], v[30:31]
	v_fmac_f32_e32 v138, v185, v1
	v_pk_fma_f32 v[34:35], v[102:103], v[18:19], v[36:37]
	v_fmac_f32_e32 v137, v184, v1
	v_pk_fma_f32 v[28:29], v[100:101], v[18:19], v[28:29]
	v_fmac_f32_e32 v136, v183, v1
	v_pk_fma_f32 v[36:37], v[98:99], v[18:19], v[38:39]
	v_fmac_f32_e32 v135, v182, v1
	v_pk_fma_f32 v[26:27], v[96:97], v[18:19], v[26:27]
	v_fmac_f32_e32 v134, v181, v1
	v_pk_fma_f32 v[202:203], v[94:95], v[18:19], v[202:203]
	v_fmac_f32_e32 v133, v180, v1
	v_pk_fma_f32 v[24:25], v[92:93], v[18:19], v[24:25]
	v_fmac_f32_e32 v5, v179, v1
	v_pk_fma_f32 v[204:205], v[90:91], v[18:19], v[204:205]
	v_fmac_f32_e32 v2, v178, v1
	v_pk_fma_f32 v[16:17], v[88:89], v[18:19], v[16:17]
	v_fmac_f32_e32 v7, v177, v1
	v_lshlrev_b32_e32 v18, 16, v201
	v_and_b32_e32 v19, 0xffff0000, v201
	v_lshlrev_b32_e32 v1, 16, v200
; #define LAS __attribute__((address_space(3)))
; __device__ __forceinline__ float bf_lo(unsigned w) { return __uint_as_float(w << 16); }
; __device__ __forceinline__ float bf_hi(unsigned w) { return __uint_as_float(w & 0xffff0000u); }
; __device__ __forceinline__ void p2_conv_unit_prompt(Frame& F, int unit, int next_pm, const ConvW& cw, size_t src_off = WS_A, size_t dst_off = WS_CACT) {
;     ...
;         for (int rg = 0; rg < CV_ROWS; rg += 8) {
;             unsigned w2[8], w1[8];
; #pragma unroll
;             for (int i = 0; i < 8; ++i) if (rg + i < CV_ROWS) { const LAS unsigned char* rp = S + (rg + i) * (DCONV * 2) + ((rg + i) < CW - 1 ? ringLo : ringHi);
;                 w2[i] = *(const LAS unsigned*)(rp + p * 2u); w1[i] = *(const LAS unsigned short*)(rp + q * 2u); }
; #pragma unroll
;             for (int i = 0; i < 8; ++i) if (rg + i < CV_ROWS) { const int rr = rg + i; const f32x2 vp = (f32x2){bf_lo(w2[i]), bf_hi(w2[i])}; const float vq = bf_lo(w1[i]);
; #pragma unroll
;                 for (int t = 0; t < 16; ++t) { const int j = rr - t; if (j >= 0 && j < CW) { ap[t] += wp[j] * vp; aq[t] += wq[j] * vq; } } }
;             __builtin_amdgcn_sched_barrier(0); }
	v_pk_fma_f32 v[38:39], v[112:113], v[18:19], v[20:21]
	v_fmac_f32_e32 v141, v189, v1
	v_pk_fma_f32 v[20:21], v[110:111], v[18:19], v[22:23]
	v_fmac_f32_e32 v140, v188, v1
	v_pk_fma_f32 v[22:23], v[108:109], v[18:19], v[32:33]
	v_fmac_f32_e32 v139, v187, v1
	v_pk_fma_f32 v[30:31], v[106:107], v[18:19], v[30:31]
	v_fmac_f32_e32 v138, v186, v1
	v_pk_fma_f32 v[32:33], v[104:105], v[18:19], v[34:35]
	v_fmac_f32_e32 v137, v185, v1
	v_pk_fma_f32 v[28:29], v[102:103], v[18:19], v[28:29]
	v_fmac_f32_e32 v136, v184, v1
	v_pk_fma_f32 v[34:35], v[100:101], v[18:19], v[36:37]
	v_fmac_f32_e32 v135, v183, v1
	v_pk_fma_f32 v[26:27], v[98:99], v[18:19], v[26:27]
	v_fmac_f32_e32 v134, v182, v1
	v_pk_fma_f32 v[200:201], v[96:97], v[18:19], v[202:203]
	v_fmac_f32_e32 v133, v181, v1
	v_pk_fma_f32 v[24:25], v[94:95], v[18:19], v[24:25]
	v_fmac_f32_e32 v5, v180, v1
	v_pk_fma_f32 v[202:203], v[92:93], v[18:19], v[204:205]
	v_fmac_f32_e32 v2, v179, v1
	v_pk_fma_f32 v[16:17], v[90:91], v[18:19], v[16:17]
	v_fmac_f32_e32 v7, v178, v1
	v_lshlrev_b32_e32 v18, 16, v199
	v_and_b32_e32 v19, 0xffff0000, v199
	v_lshlrev_b32_e32 v1, 16, v198
	v_pk_fma_f32 v[36:37], v[112:113], v[18:19], v[20:21]
	v_fmac_f32_e32 v140, v189, v1
	v_pk_fma_f32 v[20:21], v[110:111], v[18:19], v[22:23]
	v_fmac_f32_e32 v139, v188, v1
	v_pk_fma_f32 v[22:23], v[108:109], v[18:19], v[30:31]
	v_fmac_f32_e32 v138, v187, v1
	v_pk_fma_f32 v[30:31], v[106:107], v[18:19], v[32:33]
	v_fmac_f32_e32 v137, v186, v1
	v_pk_fma_f32 v[28:29], v[104:105], v[18:19], v[28:29]
	v_fmac_f32_e32 v136, v185, v1
	v_pk_fma_f32 v[32:33], v[102:103], v[18:19], v[34:35]
	v_fmac_f32_e32 v135, v184, v1
	v_pk_fma_f32 v[26:27], v[100:101], v[18:19], v[26:27]
	v_fmac_f32_e32 v134, v183, v1
	v_pk_fma_f32 v[198:199], v[98:99], v[18:19], v[200:201]
	v_fmac_f32_e32 v133, v182, v1
	v_pk_fma_f32 v[24:25], v[96:97], v[18:19], v[24:25]
	v_fmac_f32_e32 v5, v181, v1
	v_pk_fma_f32 v[200:201], v[94:95], v[18:19], v[202:203]
	v_fmac_f32_e32 v2, v180, v1
	v_pk_fma_f32 v[16:17], v[92:93], v[18:19], v[16:17]
	v_fmac_f32_e32 v7, v179, v1
	v_lshlrev_b32_e32 v18, 16, v165
	v_and_b32_e32 v19, 0xffff0000, v165
	v_lshlrev_b32_e32 v1, 16, v164
	v_pk_fma_f32 v[34:35], v[112:113], v[18:19], v[20:21]
	v_fmac_f32_e32 v139, v189, v1
	v_pk_fma_f32 v[20:21], v[110:111], v[18:19], v[22:23]
	v_fmac_f32_e32 v138, v188, v1
	v_pk_fma_f32 v[22:23], v[108:109], v[18:19], v[30:31]
	v_fmac_f32_e32 v137, v187, v1
	v_pk_fma_f32 v[28:29], v[106:107], v[18:19], v[28:29]
	v_fmac_f32_e32 v136, v186, v1
	v_pk_fma_f32 v[30:31], v[104:105], v[18:19], v[32:33]
	v_fmac_f32_e32 v135, v185, v1
	v_pk_fma_f32 v[26:27], v[102:103], v[18:19], v[26:27]
	v_fmac_f32_e32 v134, v184, v1
	v_pk_fma_f32 v[164:165], v[100:101], v[18:19], v[198:199]
	v_fmac_f32_e32 v133, v183, v1
	v_pk_fma_f32 v[24:25], v[98:99], v[18:19], v[24:25]
	v_fmac_f32_e32 v5, v182, v1
	v_pk_fma_f32 v[198:199], v[96:97], v[18:19], v[200:201]
	v_fmac_f32_e32 v2, v181, v1
	v_pk_fma_f32 v[16:17], v[94:95], v[18:19], v[16:17]
	v_fmac_f32_e32 v7, v180, v1
	v_lshlrev_b32_e32 v18, 16, v163
	v_and_b32_e32 v19, 0xffff0000, v163
	v_lshlrev_b32_e32 v1, 16, v162
	v_pk_fma_f32 v[32:33], v[112:113], v[18:19], v[20:21]
	v_fmac_f32_e32 v138, v189, v1
	v_pk_fma_f32 v[20:21], v[110:111], v[18:19], v[22:23]
	v_fmac_f32_e32 v137, v188, v1
	v_pk_fma_f32 v[22:23], v[108:109], v[18:19], v[28:29]
	v_fmac_f32_e32 v136, v187, v1
	v_pk_fma_f32 v[28:29], v[106:107], v[18:19], v[30:31]
	v_fmac_f32_e32 v135, v186, v1
	v_pk_fma_f32 v[26:27], v[104:105], v[18:19], v[26:27]
	v_fmac_f32_e32 v134, v185, v1
	v_pk_fma_f32 v[162:163], v[102:103], v[18:19], v[164:165]
	v_fmac_f32_e32 v133, v184, v1
	v_pk_fma_f32 v[24:25], v[100:101], v[18:19], v[24:25]
	v_fmac_f32_e32 v5, v183, v1
	v_pk_fma_f32 v[164:165], v[98:99], v[18:19], v[198:199]
	v_fmac_f32_e32 v2, v182, v1
	v_pk_fma_f32 v[16:17], v[96:97], v[18:19], v[16:17]
	v_fmac_f32_e32 v7, v181, v1
	v_lshlrev_b32_e32 v18, 16, v161
	v_and_b32_e32 v19, 0xffff0000, v161
	v_lshlrev_b32_e32 v1, 16, v160
	v_pk_fma_f32 v[30:31], v[112:113], v[18:19], v[20:21]
	v_fmac_f32_e32 v137, v189, v1
	v_pk_fma_f32 v[20:21], v[110:111], v[18:19], v[22:23]
	v_fmac_f32_e32 v136, v188, v1
	v_pk_fma_f32 v[22:23], v[108:109], v[18:19], v[28:29]
	v_fmac_f32_e32 v135, v187, v1
	v_pk_fma_f32 v[26:27], v[106:107], v[18:19], v[26:27]
	v_fmac_f32_e32 v134, v186, v1
	v_pk_fma_f32 v[160:161], v[104:105], v[18:19], v[162:163]
	v_fmac_f32_e32 v133, v185, v1
	v_pk_fma_f32 v[24:25], v[102:103], v[18:19], v[24:25]
	v_fmac_f32_e32 v5, v184, v1
	v_pk_fma_f32 v[162:163], v[100:101], v[18:19], v[164:165]
	v_fmac_f32_e32 v2, v183, v1
	v_pk_fma_f32 v[16:17], v[98:99], v[18:19], v[16:17]
	v_fmac_f32_e32 v7, v182, v1
	v_lshlrev_b32_e32 v18, 16, v159
	v_and_b32_e32 v19, 0xffff0000, v159
	v_lshlrev_b32_e32 v1, 16, v158
	v_pk_fma_f32 v[28:29], v[112:113], v[18:19], v[20:21]
	v_fmac_f32_e32 v136, v189, v1
	v_pk_fma_f32 v[20:21], v[110:111], v[18:19], v[22:23]
	v_fmac_f32_e32 v135, v188, v1
	v_pk_fma_f32 v[22:23], v[108:109], v[18:19], v[26:27]
	v_fmac_f32_e32 v134, v187, v1
	v_pk_fma_f32 v[158:159], v[106:107], v[18:19], v[160:161]
	v_fmac_f32_e32 v133, v186, v1
	v_pk_fma_f32 v[24:25], v[104:105], v[18:19], v[24:25]
	v_fmac_f32_e32 v5, v185, v1
	v_pk_fma_f32 v[160:161], v[102:103], v[18:19], v[162:163]
	v_fmac_f32_e32 v2, v184, v1
	v_pk_fma_f32 v[16:17], v[100:101], v[18:19], v[16:17]
	v_fmac_f32_e32 v7, v183, v1
	v_lshlrev_b32_e32 v18, 16, v157
	v_and_b32_e32 v19, 0xffff0000, v157
	v_lshlrev_b32_e32 v1, 16, v156
	v_pk_fma_f32 v[26:27], v[112:113], v[18:19], v[20:21]
	v_fmac_f32_e32 v135, v189, v1
	v_pk_fma_f32 v[20:21], v[110:111], v[18:19], v[22:23]
; #define LAS __attribute__((address_space(3)))
; #define LDS_WAIT() asm volatile("s_waitcnt lgkmcnt(0)" ::: "memory")
; __device__ __forceinline__ float bf_lo(unsigned w) { return __uint_as_float(w << 16); }
; __device__ __forceinline__ float bf_hi(unsigned w) { return __uint_as_float(w & 0xffff0000u); }
; __device__ __forceinline__ void p2_conv_unit_prompt(Frame& F, int unit, int next_pm, const ConvW& cw, size_t src_off = WS_A, size_t dst_off = WS_CACT) {
;     ...
;             for (int i = 0; i < 8; ++i) if (rg + i < CV_ROWS) { const LAS unsigned char* rp = S + (rg + i) * (DCONV * 2) + ((rg + i) < CW - 1 ? ringLo : ringHi);
;                 w2[i] = *(const LAS unsigned*)(rp + p * 2u); w1[i] = *(const LAS unsigned short*)(rp + q * 2u); }
; #pragma unroll
;             for (int i = 0; i < 8; ++i) if (rg + i < CV_ROWS) { const int rr = rg + i; const f32x2 vp = (f32x2){bf_lo(w2[i]), bf_hi(w2[i])}; const float vq = bf_lo(w1[i]);
; #pragma unroll
;                 for (int t = 0; t < 16; ++t) { const int j = rr - t; if (j >= 0 && j < CW) { ap[t] += wp[j] * vp; aq[t] += wq[j] * vq; } } }
;             __builtin_amdgcn_sched_barrier(0); }
;         LDS_WAIT(); __syncthreads();
;         if (h == 0) conv_stage_tail(F, S, rowA + 16, src_off);
;         else if (next_pm >= 0) poolmix_stage(F, next_pm);
;         float st[32];
; #pragma unroll
;         for (int t = 0; t < 16; ++t) { st[t] = (ap[t].x + ap[t].y) + aq[t]; st[16 + t] = (ap[t].x * ap[t].x + ap[t].y * ap[t].y) + aq[t] * aq[t]; }
;         float tot = 0.f;
; #pragma unroll
;         for (int i = 0; i < 32; ++i) { const float w = wave_sum(st[i]); asm volatile("v_writelane_b32 %0, %1, %2" : "+v"(tot) : "s"(w), "n"(i)); }
	v_fmac_f32_e32 v134, v188, v1
	v_pk_fma_f32 v[22:23], v[108:109], v[18:19], v[158:159]
	v_fmac_f32_e32 v133, v187, v1
	v_pk_fma_f32 v[156:157], v[106:107], v[18:19], v[24:25]
	v_fmac_f32_e32 v5, v186, v1
	v_pk_fma_f32 v[158:159], v[104:105], v[18:19], v[160:161]
	v_fmac_f32_e32 v2, v185, v1
	v_pk_fma_f32 v[16:17], v[102:103], v[18:19], v[16:17]
	v_fmac_f32_e32 v7, v184, v1
	v_lshlrev_b32_e32 v18, 16, v155
	v_and_b32_e32 v19, 0xffff0000, v155
	v_lshlrev_b32_e32 v1, 16, v154
	v_pk_fma_f32 v[24:25], v[112:113], v[18:19], v[20:21]
	v_fmac_f32_e32 v134, v189, v1
	v_pk_fma_f32 v[20:21], v[110:111], v[18:19], v[22:23]
	v_fmac_f32_e32 v133, v188, v1
	v_pk_fma_f32 v[154:155], v[108:109], v[18:19], v[156:157]
	v_fmac_f32_e32 v5, v187, v1
	v_pk_fma_f32 v[156:157], v[106:107], v[18:19], v[158:159]
	v_fmac_f32_e32 v2, v186, v1
	v_pk_fma_f32 v[16:17], v[104:105], v[18:19], v[16:17]
	v_fmac_f32_e32 v7, v185, v1
	v_lshlrev_b32_e32 v18, 16, v153
	v_and_b32_e32 v19, 0xffff0000, v153
	v_lshlrev_b32_e32 v1, 16, v152
	v_pk_fma_f32 v[22:23], v[112:113], v[18:19], v[20:21]
	v_fmac_f32_e32 v133, v189, v1
	v_pk_fma_f32 v[20:21], v[110:111], v[18:19], v[154:155]
	v_fmac_f32_e32 v5, v188, v1
	v_pk_fma_f32 v[152:153], v[108:109], v[18:19], v[156:157]
	v_fmac_f32_e32 v2, v187, v1
	v_pk_fma_f32 v[16:17], v[106:107], v[18:19], v[16:17]
	v_fmac_f32_e32 v7, v186, v1
	v_lshlrev_b32_e32 v18, 16, v151
	v_and_b32_e32 v19, 0xffff0000, v151
	v_lshlrev_b32_e32 v1, 16, v150
	v_fmac_f32_e32 v5, v189, v1
	v_pk_fma_f32 v[150:151], v[110:111], v[18:19], v[152:153]
	v_fmac_f32_e32 v2, v188, v1
	v_pk_fma_f32 v[16:17], v[108:109], v[18:19], v[16:17]
	v_fmac_f32_e32 v7, v187, v1
	v_lshlrev_b32_e32 v152, 16, v149
	v_and_b32_e32 v153, 0xffff0000, v149
	v_lshlrev_b32_e32 v1, 16, v148
	v_fmac_f32_e32 v2, v189, v1
	v_pk_fma_f32 v[16:17], v[110:111], v[152:153], v[16:17]
	v_fmac_f32_e32 v7, v188, v1
	v_lshlrev_b32_e32 v148, 16, v147
	v_and_b32_e32 v149, 0xffff0000, v147
	v_lshlrev_b32_e32 v1, 16, v146
	v_pk_mul_f32 v[146:147], v[40:41], v[40:41]
	v_pk_fma_f32 v[16:17], v[112:113], v[148:149], v[16:17]
	v_add_f32_e32 v148, v146, v147
	v_add_f32_e32 v146, v46, v47
	v_add_f32_e32 v149, v144, v146
	v_pk_mul_f32 v[146:147], v[46:47], v[46:47]
	v_pk_fma_f32 v[20:21], v[112:113], v[18:19], v[20:21]
	v_pk_fma_f32 v[18:19], v[112:113], v[152:153], v[150:151]
	v_add_f32_e32 v150, v146, v147
	v_add_f32_e32 v146, v44, v45
	v_add_f32_e32 v151, v143, v146
	v_pk_mul_f32 v[146:147], v[44:45], v[44:45]
	v_fmac_f32_e32 v7, v189, v1
	v_add_f32_e32 v152, v146, v147
	v_add_f32_e32 v146, v42, v43
	v_add_f32_e32 v153, v142, v146
	v_pk_mul_f32 v[146:147], v[42:43], v[42:43]
	v_add_f32_e32 v1, v40, v41
	v_add_f32_e32 v154, v146, v147
	v_add_f32_e32 v146, v38, v39
	v_add_f32_e32 v155, v141, v146
	v_pk_mul_f32 v[146:147], v[38:39], v[38:39]
	v_add_f32_e32 v1, v145, v1
	v_add_f32_e32 v156, v146, v147
	v_add_f32_e32 v146, v36, v37
	v_add_f32_e32 v157, v140, v146
	v_pk_mul_f32 v[146:147], v[36:37], v[36:37]
	v_add_f32_dpp v1, v1, v1 quad_perm:[1,0,3,2] row_mask:0xf bank_mask:0xf bound_ctrl:1
	v_add_f32_e32 v158, v146, v147
	v_add_f32_e32 v146, v34, v35
	v_add_f32_e32 v159, v139, v146
	v_pk_mul_f32 v[146:147], v[34:35], v[34:35]
	v_add_f32_dpp v1, v1, v1 quad_perm:[2,3,0,1] row_mask:0xf bank_mask:0xf bound_ctrl:1
	v_add_f32_e32 v160, v146, v147
	v_add_f32_e32 v146, v32, v33
	v_add_f32_e32 v161, v138, v146
	v_pk_mul_f32 v[146:147], v[32:33], v[32:33]
	v_add_f32_dpp v1, v1, v1 row_half_mirror row_mask:0xf bank_mask:0xf bound_ctrl:1
	v_add_f32_e32 v162, v146, v147
	v_add_f32_e32 v146, v30, v31
	v_add_f32_e32 v163, v137, v146
	v_pk_mul_f32 v[146:147], v[30:31], v[30:31]
	v_add_f32_dpp v1, v1, v1 row_mirror row_mask:0xf bank_mask:0xf bound_ctrl:1
	v_add_f32_e32 v164, v146, v147
	v_add_f32_e32 v146, v28, v29
	v_add_f32_e32 v165, v136, v146
	v_pk_mul_f32 v[146:147], v[28:29], v[28:29]
	v_fmac_f32_e32 v148, v145, v145
	v_add_f32_e32 v198, v146, v147
	v_add_f32_e32 v146, v26, v27
	v_add_f32_e32 v199, v135, v146
	v_pk_mul_f32 v[146:147], v[26:27], v[26:27]
	v_fmac_f32_e32 v150, v144, v144
	v_add_f32_e32 v200, v146, v147
	v_add_f32_e32 v146, v24, v25
	v_add_f32_e32 v201, v134, v146
	v_pk_mul_f32 v[146:147], v[24:25], v[24:25]
	v_fmac_f32_e32 v152, v143, v143
	v_add_f32_e32 v202, v146, v147
	v_add_f32_e32 v146, v22, v23
	v_add_f32_e32 v203, v133, v146
	v_pk_mul_f32 v[146:147], v[22:23], v[22:23]
	v_fmac_f32_e32 v154, v142, v142
	v_add_f32_e32 v204, v146, v147
	v_add_f32_e32 v146, v20, v21
	v_add_f32_e32 v205, v5, v146
	v_pk_mul_f32 v[146:147], v[20:21], v[20:21]
	v_fmac_f32_e32 v156, v141, v141
	v_add_f32_e32 v206, v146, v147
	v_add_f32_e32 v146, v18, v19
	v_add_f32_e32 v207, v2, v146
	v_pk_mul_f32 v[146:147], v[18:19], v[18:19]
	v_fmac_f32_e32 v158, v140, v140
	v_add_f32_e32 v208, v146, v147
	v_add_f32_e32 v146, v16, v17
	v_add_f32_e32 v209, v7, v146
	v_pk_mul_f32 v[146:147], v[16:17], v[16:17]
	v_fmac_f32_e32 v160, v139, v139
	v_add_f32_e32 v147, v146, v147
	v_mov_b32_e32 v146, v3
	v_fmac_f32_e32 v162, v138, v138
	v_fmac_f32_e32 v164, v137, v137
	v_mov_b32_dpp v146, v1 row_bcast:15 row_mask:0xa bank_mask:0xf
	v_add_f32_e32 v1, v1, v146
	v_mov_b32_e32 v146, v3
	v_fmac_f32_e32 v198, v136, v136
	v_fmac_f32_e32 v200, v135, v135
	v_mov_b32_dpp v146, v1 row_bcast:31 row_mask:0xc bank_mask:0xf
	v_add_f32_e32 v1, v1, v146
	v_mov_b32_e32 v146, v3
	v_readlane_b32 s12, v1, 63
	v_fmac_f32_e32 v202, v134, v134
	v_fmac_f32_e32 v204, v133, v133
	v_fmac_f32_e32 v206, v5, v5
	v_fmac_f32_e32 v208, v2, v2
	v_fmac_f32_e32 v147, v7, v7
	v_writelane_b32 v146, s12, 0
	v_add_f32_dpp v149, v149, v149 quad_perm:[1,0,3,2] row_mask:0xf bank_mask:0xf bound_ctrl:1
; template <int CTRL, int RM> __device__ __forceinline__ float dppf(float v) { return __builtin_bit_cast(float, __builtin_amdgcn_update_dpp(0, __builtin_bit_cast(int, v), CTRL, RM, 0xF, false)); }
; __device__ __forceinline__ float row_sum_dpp(float v) {
;     v += dppf<0xB1, 0xF>(v); v += dppf<0x4E, 0xF>(v); v += dppf<0x141, 0xF>(v); v += dppf<0x140, 0xF>(v); return v; }
; __device__ __forceinline__ float half_sum_dpp(float v) {
;     v = row_sum_dpp(v); v += dppf<0x142, 0xA>(v); return v; }
; __device__ __forceinline__ float wave_sum(float v) {
;     v = half_sum_dpp(v); v += dppf<0x143, 0xC>(v);
;     return __builtin_bit_cast(float, __builtin_amdgcn_readlane(__builtin_bit_cast(int, v), 63)); }
; __device__ __forceinline__ void p2_conv_unit_prompt(Frame& F, int unit, int next_pm, const ConvW& cw, size_t src_off = WS_A, size_t dst_off = WS_CACT) {
;     ...
;         for (int i = 0; i < 32; ++i) { const float w = wave_sum(st[i]); asm volatile("v_writelane_b32 %0, %1, %2" : "+v"(tot) : "s"(w), "n"(i)); }
	v_add_f32_dpp v151, v151, v151 quad_perm:[1,0,3,2] row_mask:0xf bank_mask:0xf bound_ctrl:1
	v_add_f32_dpp v153, v153, v153 quad_perm:[1,0,3,2] row_mask:0xf bank_mask:0xf bound_ctrl:1
	v_add_f32_dpp v155, v155, v155 quad_perm:[1,0,3,2] row_mask:0xf bank_mask:0xf bound_ctrl:1
	v_add_f32_dpp v157, v157, v157 quad_perm:[1,0,3,2] row_mask:0xf bank_mask:0xf bound_ctrl:1
	v_add_f32_dpp v159, v159, v159 quad_perm:[1,0,3,2] row_mask:0xf bank_mask:0xf bound_ctrl:1
	v_add_f32_dpp v161, v161, v161 quad_perm:[1,0,3,2] row_mask:0xf bank_mask:0xf bound_ctrl:1
	v_add_f32_dpp v163, v163, v163 quad_perm:[1,0,3,2] row_mask:0xf bank_mask:0xf bound_ctrl:1
	v_add_f32_dpp v165, v165, v165 quad_perm:[1,0,3,2] row_mask:0xf bank_mask:0xf bound_ctrl:1
	v_add_f32_dpp v199, v199, v199 quad_perm:[1,0,3,2] row_mask:0xf bank_mask:0xf bound_ctrl:1
	v_add_f32_dpp v201, v201, v201 quad_perm:[1,0,3,2] row_mask:0xf bank_mask:0xf bound_ctrl:1
	v_add_f32_dpp v203, v203, v203 quad_perm:[1,0,3,2] row_mask:0xf bank_mask:0xf bound_ctrl:1
	v_add_f32_dpp v205, v205, v205 quad_perm:[1,0,3,2] row_mask:0xf bank_mask:0xf bound_ctrl:1
	v_add_f32_dpp v207, v207, v207 quad_perm:[1,0,3,2] row_mask:0xf bank_mask:0xf bound_ctrl:1
	v_add_f32_dpp v209, v209, v209 quad_perm:[1,0,3,2] row_mask:0xf bank_mask:0xf bound_ctrl:1
	v_add_f32_dpp v148, v148, v148 quad_perm:[1,0,3,2] row_mask:0xf bank_mask:0xf bound_ctrl:1
	v_add_f32_dpp v150, v150, v150 quad_perm:[1,0,3,2] row_mask:0xf bank_mask:0xf bound_ctrl:1
	v_add_f32_dpp v152, v152, v152 quad_perm:[1,0,3,2] row_mask:0xf bank_mask:0xf bound_ctrl:1
	v_add_f32_dpp v154, v154, v154 quad_perm:[1,0,3,2] row_mask:0xf bank_mask:0xf bound_ctrl:1
	v_add_f32_dpp v156, v156, v156 quad_perm:[1,0,3,2] row_mask:0xf bank_mask:0xf bound_ctrl:1
	v_add_f32_dpp v158, v158, v158 quad_perm:[1,0,3,2] row_mask:0xf bank_mask:0xf bound_ctrl:1
	v_add_f32_dpp v160, v160, v160 quad_perm:[1,0,3,2] row_mask:0xf bank_mask:0xf bound_ctrl:1
	v_add_f32_dpp v162, v162, v162 quad_perm:[1,0,3,2] row_mask:0xf bank_mask:0xf bound_ctrl:1
	v_add_f32_dpp v164, v164, v164 quad_perm:[1,0,3,2] row_mask:0xf bank_mask:0xf bound_ctrl:1
	v_add_f32_dpp v198, v198, v198 quad_perm:[1,0,3,2] row_mask:0xf bank_mask:0xf bound_ctrl:1
	v_add_f32_dpp v200, v200, v200 quad_perm:[1,0,3,2] row_mask:0xf bank_mask:0xf bound_ctrl:1
	v_add_f32_dpp v202, v202, v202 quad_perm:[1,0,3,2] row_mask:0xf bank_mask:0xf bound_ctrl:1
	v_add_f32_dpp v204, v204, v204 quad_perm:[1,0,3,2] row_mask:0xf bank_mask:0xf bound_ctrl:1
	v_add_f32_dpp v206, v206, v206 quad_perm:[1,0,3,2] row_mask:0xf bank_mask:0xf bound_ctrl:1
	v_add_f32_dpp v208, v208, v208 quad_perm:[1,0,3,2] row_mask:0xf bank_mask:0xf bound_ctrl:1
	v_add_f32_dpp v147, v147, v147 quad_perm:[1,0,3,2] row_mask:0xf bank_mask:0xf bound_ctrl:1
	v_add_f32_dpp v149, v149, v149 quad_perm:[2,3,0,1] row_mask:0xf bank_mask:0xf bound_ctrl:1
	v_add_f32_dpp v151, v151, v151 quad_perm:[2,3,0,1] row_mask:0xf bank_mask:0xf bound_ctrl:1
	v_add_f32_dpp v153, v153, v153 quad_perm:[2,3,0,1] row_mask:0xf bank_mask:0xf bound_ctrl:1
	v_add_f32_dpp v155, v155, v155 quad_perm:[2,3,0,1] row_mask:0xf bank_mask:0xf bound_ctrl:1
	v_add_f32_dpp v157, v157, v157 quad_perm:[2,3,0,1] row_mask:0xf bank_mask:0xf bound_ctrl:1
	v_add_f32_dpp v159, v159, v159 quad_perm:[2,3,0,1] row_mask:0xf bank_mask:0xf bound_ctrl:1
	v_add_f32_dpp v161, v161, v161 quad_perm:[2,3,0,1] row_mask:0xf bank_mask:0xf bound_ctrl:1
	v_add_f32_dpp v163, v163, v163 quad_perm:[2,3,0,1] row_mask:0xf bank_mask:0xf bound_ctrl:1
	v_add_f32_dpp v165, v165, v165 quad_perm:[2,3,0,1] row_mask:0xf bank_mask:0xf bound_ctrl:1
	v_add_f32_dpp v199, v199, v199 quad_perm:[2,3,0,1] row_mask:0xf bank_mask:0xf bound_ctrl:1
	v_add_f32_dpp v201, v201, v201 quad_perm:[2,3,0,1] row_mask:0xf bank_mask:0xf bound_ctrl:1
	v_add_f32_dpp v203, v203, v203 quad_perm:[2,3,0,1] row_mask:0xf bank_mask:0xf bound_ctrl:1
	v_add_f32_dpp v205, v205, v205 quad_perm:[2,3,0,1] row_mask:0xf bank_mask:0xf bound_ctrl:1
	v_add_f32_dpp v207, v207, v207 quad_perm:[2,3,0,1] row_mask:0xf bank_mask:0xf bound_ctrl:1
	v_add_f32_dpp v209, v209, v209 quad_perm:[2,3,0,1] row_mask:0xf bank_mask:0xf bound_ctrl:1
	v_add_f32_dpp v148, v148, v148 quad_perm:[2,3,0,1] row_mask:0xf bank_mask:0xf bound_ctrl:1
	v_add_f32_dpp v150, v150, v150 quad_perm:[2,3,0,1] row_mask:0xf bank_mask:0xf bound_ctrl:1
	v_add_f32_dpp v152, v152, v152 quad_perm:[2,3,0,1] row_mask:0xf bank_mask:0xf bound_ctrl:1
	v_add_f32_dpp v154, v154, v154 quad_perm:[2,3,0,1] row_mask:0xf bank_mask:0xf bound_ctrl:1
	v_add_f32_dpp v156, v156, v156 quad_perm:[2,3,0,1] row_mask:0xf bank_mask:0xf bound_ctrl:1
	v_add_f32_dpp v158, v158, v158 quad_perm:[2,3,0,1] row_mask:0xf bank_mask:0xf bound_ctrl:1
	v_add_f32_dpp v160, v160, v160 quad_perm:[2,3,0,1] row_mask:0xf bank_mask:0xf bound_ctrl:1
	v_add_f32_dpp v162, v162, v162 quad_perm:[2,3,0,1] row_mask:0xf bank_mask:0xf bound_ctrl:1
	v_add_f32_dpp v164, v164, v164 quad_perm:[2,3,0,1] row_mask:0xf bank_mask:0xf bound_ctrl:1
	v_add_f32_dpp v198, v198, v198 quad_perm:[2,3,0,1] row_mask:0xf bank_mask:0xf bound_ctrl:1
	v_add_f32_dpp v200, v200, v200 quad_perm:[2,3,0,1] row_mask:0xf bank_mask:0xf bound_ctrl:1
	v_add_f32_dpp v202, v202, v202 quad_perm:[2,3,0,1] row_mask:0xf bank_mask:0xf bound_ctrl:1
	v_add_f32_dpp v204, v204, v204 quad_perm:[2,3,0,1] row_mask:0xf bank_mask:0xf bound_ctrl:1
	v_add_f32_dpp v206, v206, v206 quad_perm:[2,3,0,1] row_mask:0xf bank_mask:0xf bound_ctrl:1
	v_add_f32_dpp v208, v208, v208 quad_perm:[2,3,0,1] row_mask:0xf bank_mask:0xf bound_ctrl:1
	v_add_f32_dpp v147, v147, v147 quad_perm:[2,3,0,1] row_mask:0xf bank_mask:0xf bound_ctrl:1
; template <int CTRL, int RM> __device__ __forceinline__ float dppf(float v) { return __builtin_bit_cast(float, __builtin_amdgcn_update_dpp(0, __builtin_bit_cast(int, v), CTRL, RM, 0xF, false)); }
; __device__ __forceinline__ float row_sum_dpp(float v) {
;     v += dppf<0xB1, 0xF>(v); v += dppf<0x4E, 0xF>(v); v += dppf<0x141, 0xF>(v); v += dppf<0x140, 0xF>(v); return v; }
; __device__ __forceinline__ float half_sum_dpp(float v) {
;     v = row_sum_dpp(v); v += dppf<0x142, 0xA>(v); return v; }
; __device__ __forceinline__ float wave_sum(float v) {
;     v = half_sum_dpp(v); v += dppf<0x143, 0xC>(v);
;     return __builtin_bit_cast(float, __builtin_amdgcn_readlane(__builtin_bit_cast(int, v), 63)); }
; __device__ __forceinline__ void p2_conv_unit_prompt(Frame& F, int unit, int next_pm, const ConvW& cw, size_t src_off = WS_A, size_t dst_off = WS_CACT) {
;     ...
;         for (int i = 0; i < 32; ++i) { const float w = wave_sum(st[i]); asm volatile("v_writelane_b32 %0, %1, %2" : "+v"(tot) : "s"(w), "n"(i)); }
	v_add_f32_dpp v149, v149, v149 row_half_mirror row_mask:0xf bank_mask:0xf bound_ctrl:1
	v_add_f32_dpp v151, v151, v151 row_half_mirror row_mask:0xf bank_mask:0xf bound_ctrl:1
	v_add_f32_dpp v153, v153, v153 row_half_mirror row_mask:0xf bank_mask:0xf bound_ctrl:1
	v_add_f32_dpp v155, v155, v155 row_half_mirror row_mask:0xf bank_mask:0xf bound_ctrl:1
	v_add_f32_dpp v157, v157, v157 row_half_mirror row_mask:0xf bank_mask:0xf bound_ctrl:1
	v_add_f32_dpp v159, v159, v159 row_half_mirror row_mask:0xf bank_mask:0xf bound_ctrl:1
	v_add_f32_dpp v161, v161, v161 row_half_mirror row_mask:0xf bank_mask:0xf bound_ctrl:1
	v_add_f32_dpp v163, v163, v163 row_half_mirror row_mask:0xf bank_mask:0xf bound_ctrl:1
	v_add_f32_dpp v165, v165, v165 row_half_mirror row_mask:0xf bank_mask:0xf bound_ctrl:1
	v_add_f32_dpp v199, v199, v199 row_half_mirror row_mask:0xf bank_mask:0xf bound_ctrl:1
	v_add_f32_dpp v201, v201, v201 row_half_mirror row_mask:0xf bank_mask:0xf bound_ctrl:1
	v_add_f32_dpp v203, v203, v203 row_half_mirror row_mask:0xf bank_mask:0xf bound_ctrl:1
	v_add_f32_dpp v205, v205, v205 row_half_mirror row_mask:0xf bank_mask:0xf bound_ctrl:1
	v_add_f32_dpp v207, v207, v207 row_half_mirror row_mask:0xf bank_mask:0xf bound_ctrl:1
	v_add_f32_dpp v209, v209, v209 row_half_mirror row_mask:0xf bank_mask:0xf bound_ctrl:1
	v_add_f32_dpp v148, v148, v148 row_half_mirror row_mask:0xf bank_mask:0xf bound_ctrl:1
	v_add_f32_dpp v150, v150, v150 row_half_mirror row_mask:0xf bank_mask:0xf bound_ctrl:1
	v_add_f32_dpp v152, v152, v152 row_half_mirror row_mask:0xf bank_mask:0xf bound_ctrl:1
	v_add_f32_dpp v154, v154, v154 row_half_mirror row_mask:0xf bank_mask:0xf bound_ctrl:1
	v_add_f32_dpp v156, v156, v156 row_half_mirror row_mask:0xf bank_mask:0xf bound_ctrl:1
	v_add_f32_dpp v158, v158, v158 row_half_mirror row_mask:0xf bank_mask:0xf bound_ctrl:1
	v_add_f32_dpp v160, v160, v160 row_half_mirror row_mask:0xf bank_mask:0xf bound_ctrl:1
	v_add_f32_dpp v162, v162, v162 row_half_mirror row_mask:0xf bank_mask:0xf bound_ctrl:1
	v_add_f32_dpp v164, v164, v164 row_half_mirror row_mask:0xf bank_mask:0xf bound_ctrl:1
	v_add_f32_dpp v198, v198, v198 row_half_mirror row_mask:0xf bank_mask:0xf bound_ctrl:1
	v_add_f32_dpp v200, v200, v200 row_half_mirror row_mask:0xf bank_mask:0xf bound_ctrl:1
	v_add_f32_dpp v202, v202, v202 row_half_mirror row_mask:0xf bank_mask:0xf bound_ctrl:1
	v_add_f32_dpp v204, v204, v204 row_half_mirror row_mask:0xf bank_mask:0xf bound_ctrl:1
	v_add_f32_dpp v206, v206, v206 row_half_mirror row_mask:0xf bank_mask:0xf bound_ctrl:1
	v_add_f32_dpp v208, v208, v208 row_half_mirror row_mask:0xf bank_mask:0xf bound_ctrl:1
	v_add_f32_dpp v147, v147, v147 row_half_mirror row_mask:0xf bank_mask:0xf bound_ctrl:1
	v_add_f32_dpp v149, v149, v149 row_mirror row_mask:0xf bank_mask:0xf bound_ctrl:1
	v_add_f32_dpp v151, v151, v151 row_mirror row_mask:0xf bank_mask:0xf bound_ctrl:1
	v_add_f32_dpp v153, v153, v153 row_mirror row_mask:0xf bank_mask:0xf bound_ctrl:1
	v_add_f32_dpp v155, v155, v155 row_mirror row_mask:0xf bank_mask:0xf bound_ctrl:1
	v_add_f32_dpp v157, v157, v157 row_mirror row_mask:0xf bank_mask:0xf bound_ctrl:1
	v_add_f32_dpp v159, v159, v159 row_mirror row_mask:0xf bank_mask:0xf bound_ctrl:1
	v_add_f32_dpp v161, v161, v161 row_mirror row_mask:0xf bank_mask:0xf bound_ctrl:1
	v_add_f32_dpp v163, v163, v163 row_mirror row_mask:0xf bank_mask:0xf bound_ctrl:1
	v_add_f32_dpp v165, v165, v165 row_mirror row_mask:0xf bank_mask:0xf bound_ctrl:1
	v_add_f32_dpp v199, v199, v199 row_mirror row_mask:0xf bank_mask:0xf bound_ctrl:1
	v_add_f32_dpp v201, v201, v201 row_mirror row_mask:0xf bank_mask:0xf bound_ctrl:1
	v_add_f32_dpp v203, v203, v203 row_mirror row_mask:0xf bank_mask:0xf bound_ctrl:1
	v_add_f32_dpp v205, v205, v205 row_mirror row_mask:0xf bank_mask:0xf bound_ctrl:1
	v_add_f32_dpp v207, v207, v207 row_mirror row_mask:0xf bank_mask:0xf bound_ctrl:1
	v_add_f32_dpp v209, v209, v209 row_mirror row_mask:0xf bank_mask:0xf bound_ctrl:1
	v_add_f32_dpp v148, v148, v148 row_mirror row_mask:0xf bank_mask:0xf bound_ctrl:1
	v_add_f32_dpp v150, v150, v150 row_mirror row_mask:0xf bank_mask:0xf bound_ctrl:1
	v_add_f32_dpp v152, v152, v152 row_mirror row_mask:0xf bank_mask:0xf bound_ctrl:1
	v_add_f32_dpp v154, v154, v154 row_mirror row_mask:0xf bank_mask:0xf bound_ctrl:1
	v_add_f32_dpp v156, v156, v156 row_mirror row_mask:0xf bank_mask:0xf bound_ctrl:1
	v_add_f32_dpp v158, v158, v158 row_mirror row_mask:0xf bank_mask:0xf bound_ctrl:1
	v_add_f32_dpp v160, v160, v160 row_mirror row_mask:0xf bank_mask:0xf bound_ctrl:1
	v_add_f32_dpp v162, v162, v162 row_mirror row_mask:0xf bank_mask:0xf bound_ctrl:1
	v_add_f32_dpp v164, v164, v164 row_mirror row_mask:0xf bank_mask:0xf bound_ctrl:1
	v_add_f32_dpp v198, v198, v198 row_mirror row_mask:0xf bank_mask:0xf bound_ctrl:1
	v_add_f32_dpp v200, v200, v200 row_mirror row_mask:0xf bank_mask:0xf bound_ctrl:1
	v_add_f32_dpp v202, v202, v202 row_mirror row_mask:0xf bank_mask:0xf bound_ctrl:1
	v_add_f32_dpp v204, v204, v204 row_mirror row_mask:0xf bank_mask:0xf bound_ctrl:1
	v_add_f32_dpp v206, v206, v206 row_mirror row_mask:0xf bank_mask:0xf bound_ctrl:1
	v_add_f32_dpp v208, v208, v208 row_mirror row_mask:0xf bank_mask:0xf bound_ctrl:1
	v_add_f32_dpp v147, v147, v147 row_mirror row_mask:0xf bank_mask:0xf bound_ctrl:1
	v_add_f32_dpp v149, v149, v149 row_bcast:15 row_mask:0xa bank_mask:0xf
	v_add_f32_dpp v151, v151, v151 row_bcast:15 row_mask:0xa bank_mask:0xf
	v_add_f32_dpp v153, v153, v153 row_bcast:15 row_mask:0xa bank_mask:0xf
	v_add_f32_dpp v155, v155, v155 row_bcast:15 row_mask:0xa bank_mask:0xf
	v_add_f32_dpp v157, v157, v157 row_bcast:15 row_mask:0xa bank_mask:0xf
; #define LDS_WAIT() asm volatile("s_waitcnt lgkmcnt(0)" ::: "memory")
; template <int CTRL, int RM> __device__ __forceinline__ float dppf(float v) { return __builtin_bit_cast(float, __builtin_amdgcn_update_dpp(0, __builtin_bit_cast(int, v), CTRL, RM, 0xF, false)); }
; __device__ __forceinline__ float row_sum_dpp(float v) {
;     v += dppf<0xB1, 0xF>(v); v += dppf<0x4E, 0xF>(v); v += dppf<0x141, 0xF>(v); v += dppf<0x140, 0xF>(v); return v; }
; __device__ __forceinline__ float half_sum_dpp(float v) {
;     v = row_sum_dpp(v); v += dppf<0x142, 0xA>(v); return v; }
; __device__ __forceinline__ float wave_sum(float v) {
;     v = half_sum_dpp(v); v += dppf<0x143, 0xC>(v);
;     return __builtin_bit_cast(float, __builtin_amdgcn_readlane(__builtin_bit_cast(int, v), 63)); }
; __device__ __forceinline__ void p2_conv_unit_prompt(Frame& F, int unit, int next_pm, const ConvW& cw, size_t src_off = WS_A, size_t dst_off = WS_CACT) {
;     ...
;         for (int i = 0; i < 32; ++i) { const float w = wave_sum(st[i]); asm volatile("v_writelane_b32 %0, %1, %2" : "+v"(tot) : "s"(w), "n"(i)); }
;         if (ln < 32u) WPT[F.wave * 32 + (int)ln] = tot;
;         LDS_WAIT(); __syncthreads();
	v_add_f32_dpp v159, v159, v159 row_bcast:15 row_mask:0xa bank_mask:0xf
	v_add_f32_dpp v161, v161, v161 row_bcast:15 row_mask:0xa bank_mask:0xf
	v_add_f32_dpp v163, v163, v163 row_bcast:15 row_mask:0xa bank_mask:0xf
	v_add_f32_dpp v165, v165, v165 row_bcast:15 row_mask:0xa bank_mask:0xf
	v_add_f32_dpp v199, v199, v199 row_bcast:15 row_mask:0xa bank_mask:0xf
	v_add_f32_dpp v201, v201, v201 row_bcast:15 row_mask:0xa bank_mask:0xf
	v_add_f32_dpp v203, v203, v203 row_bcast:15 row_mask:0xa bank_mask:0xf
	v_add_f32_dpp v205, v205, v205 row_bcast:15 row_mask:0xa bank_mask:0xf
	v_add_f32_dpp v207, v207, v207 row_bcast:15 row_mask:0xa bank_mask:0xf
	v_add_f32_dpp v209, v209, v209 row_bcast:15 row_mask:0xa bank_mask:0xf
	v_add_f32_dpp v148, v148, v148 row_bcast:15 row_mask:0xa bank_mask:0xf
	v_add_f32_dpp v150, v150, v150 row_bcast:15 row_mask:0xa bank_mask:0xf
	v_add_f32_dpp v152, v152, v152 row_bcast:15 row_mask:0xa bank_mask:0xf
	v_add_f32_dpp v154, v154, v154 row_bcast:15 row_mask:0xa bank_mask:0xf
	v_add_f32_dpp v156, v156, v156 row_bcast:15 row_mask:0xa bank_mask:0xf
	v_add_f32_dpp v158, v158, v158 row_bcast:15 row_mask:0xa bank_mask:0xf
	v_add_f32_dpp v160, v160, v160 row_bcast:15 row_mask:0xa bank_mask:0xf
	v_add_f32_dpp v162, v162, v162 row_bcast:15 row_mask:0xa bank_mask:0xf
	v_add_f32_dpp v164, v164, v164 row_bcast:15 row_mask:0xa bank_mask:0xf
	v_add_f32_dpp v198, v198, v198 row_bcast:15 row_mask:0xa bank_mask:0xf
	v_add_f32_dpp v200, v200, v200 row_bcast:15 row_mask:0xa bank_mask:0xf
	v_add_f32_dpp v202, v202, v202 row_bcast:15 row_mask:0xa bank_mask:0xf
	v_add_f32_dpp v204, v204, v204 row_bcast:15 row_mask:0xa bank_mask:0xf
	v_add_f32_dpp v206, v206, v206 row_bcast:15 row_mask:0xa bank_mask:0xf
	v_add_f32_dpp v208, v208, v208 row_bcast:15 row_mask:0xa bank_mask:0xf
	v_add_f32_dpp v147, v147, v147 row_bcast:15 row_mask:0xa bank_mask:0xf
	v_add_f32_dpp v149, v149, v149 row_bcast:31 row_mask:0xc bank_mask:0xf
	v_add_f32_dpp v151, v151, v151 row_bcast:31 row_mask:0xc bank_mask:0xf
	v_add_f32_dpp v153, v153, v153 row_bcast:31 row_mask:0xc bank_mask:0xf
	v_add_f32_dpp v155, v155, v155 row_bcast:31 row_mask:0xc bank_mask:0xf
	v_add_f32_dpp v157, v157, v157 row_bcast:31 row_mask:0xc bank_mask:0xf
	v_add_f32_dpp v159, v159, v159 row_bcast:31 row_mask:0xc bank_mask:0xf
	v_add_f32_dpp v161, v161, v161 row_bcast:31 row_mask:0xc bank_mask:0xf
	v_add_f32_dpp v163, v163, v163 row_bcast:31 row_mask:0xc bank_mask:0xf
	v_add_f32_dpp v165, v165, v165 row_bcast:31 row_mask:0xc bank_mask:0xf
	v_add_f32_dpp v199, v199, v199 row_bcast:31 row_mask:0xc bank_mask:0xf
	v_add_f32_dpp v201, v201, v201 row_bcast:31 row_mask:0xc bank_mask:0xf
	v_add_f32_dpp v203, v203, v203 row_bcast:31 row_mask:0xc bank_mask:0xf
	v_add_f32_dpp v205, v205, v205 row_bcast:31 row_mask:0xc bank_mask:0xf
	v_add_f32_dpp v207, v207, v207 row_bcast:31 row_mask:0xc bank_mask:0xf
	v_add_f32_dpp v209, v209, v209 row_bcast:31 row_mask:0xc bank_mask:0xf
	v_add_f32_dpp v148, v148, v148 row_bcast:31 row_mask:0xc bank_mask:0xf
	v_add_f32_dpp v150, v150, v150 row_bcast:31 row_mask:0xc bank_mask:0xf
	v_add_f32_dpp v152, v152, v152 row_bcast:31 row_mask:0xc bank_mask:0xf
	v_add_f32_dpp v154, v154, v154 row_bcast:31 row_mask:0xc bank_mask:0xf
	v_add_f32_dpp v156, v156, v156 row_bcast:31 row_mask:0xc bank_mask:0xf
	v_add_f32_dpp v158, v158, v158 row_bcast:31 row_mask:0xc bank_mask:0xf
	v_add_f32_dpp v160, v160, v160 row_bcast:31 row_mask:0xc bank_mask:0xf
	v_add_f32_dpp v162, v162, v162 row_bcast:31 row_mask:0xc bank_mask:0xf
	v_add_f32_dpp v164, v164, v164 row_bcast:31 row_mask:0xc bank_mask:0xf
	v_add_f32_dpp v198, v198, v198 row_bcast:31 row_mask:0xc bank_mask:0xf
	v_add_f32_dpp v200, v200, v200 row_bcast:31 row_mask:0xc bank_mask:0xf
	v_add_f32_dpp v202, v202, v202 row_bcast:31 row_mask:0xc bank_mask:0xf
	v_add_f32_dpp v204, v204, v204 row_bcast:31 row_mask:0xc bank_mask:0xf
	v_add_f32_dpp v206, v206, v206 row_bcast:31 row_mask:0xc bank_mask:0xf
	v_add_f32_dpp v208, v208, v208 row_bcast:31 row_mask:0xc bank_mask:0xf
	v_add_f32_dpp v147, v147, v147 row_bcast:31 row_mask:0xc bank_mask:0xf
	v_readlane_b32 s98, v149, 63
	v_readlane_b32 s99, v151, 63
	v_readlane_b32 s100, v153, 63
	v_readlane_b32 s101, v155, 63
	v_writelane_b32 v146, s98, 1
	v_writelane_b32 v146, s99, 2
	v_writelane_b32 v146, s100, 3
	v_writelane_b32 v146, s101, 4
	v_readlane_b32 s98, v157, 63
	v_readlane_b32 s99, v159, 63
	v_readlane_b32 s100, v161, 63
	v_readlane_b32 s101, v163, 63
	v_writelane_b32 v146, s98, 5
	v_writelane_b32 v146, s99, 6
	v_writelane_b32 v146, s100, 7
	v_writelane_b32 v146, s101, 8
	v_readlane_b32 s98, v165, 63
	v_readlane_b32 s99, v199, 63
	v_readlane_b32 s100, v201, 63
	v_readlane_b32 s101, v203, 63
	v_writelane_b32 v146, s98, 9
	v_writelane_b32 v146, s99, 10
	v_writelane_b32 v146, s100, 11
	v_writelane_b32 v146, s101, 12
	v_readlane_b32 s98, v205, 63
	v_readlane_b32 s99, v207, 63
	v_readlane_b32 s100, v209, 63
	v_readlane_b32 s101, v148, 63
	v_writelane_b32 v146, s98, 13
	v_writelane_b32 v146, s99, 14
	v_writelane_b32 v146, s100, 15
	v_writelane_b32 v146, s101, 16
	v_readlane_b32 s98, v150, 63
	v_readlane_b32 s99, v152, 63
	v_readlane_b32 s100, v154, 63
	v_readlane_b32 s101, v156, 63
	v_writelane_b32 v146, s98, 17
	v_writelane_b32 v146, s99, 18
	v_writelane_b32 v146, s100, 19
	v_writelane_b32 v146, s101, 20
	v_readlane_b32 s98, v158, 63
	v_readlane_b32 s99, v160, 63
	v_readlane_b32 s100, v162, 63
	v_readlane_b32 s101, v164, 63
	v_writelane_b32 v146, s98, 21
	v_writelane_b32 v146, s99, 22
	v_writelane_b32 v146, s100, 23
	v_writelane_b32 v146, s101, 24
	v_readlane_b32 s98, v198, 63
	v_readlane_b32 s99, v200, 63
	v_readlane_b32 s100, v202, 63
	v_readlane_b32 s101, v204, 63
	v_writelane_b32 v146, s98, 25
	v_writelane_b32 v146, s99, 26
	v_writelane_b32 v146, s100, 27
	v_writelane_b32 v146, s101, 28
	v_readlane_b32 s98, v206, 63
	v_readlane_b32 s99, v208, 63
	v_readlane_b32 s100, v147, 63
	v_writelane_b32 v146, s98, 29
	v_writelane_b32 v146, s99, 30
	v_writelane_b32 v146, s100, 31
	v_mov_b32_e32 v149, v3
	s_and_saveexec_b64 s[12:13], s[10:11]
	ds_write_b32 v132, v146
	s_or_b64 exec, exec, s[12:13]
	s_waitcnt lgkmcnt(0)
	s_cmp_eq_u32 s76, 0
	s_cbranch_scc1 .Lcs_novm
	s_waitcnt vmcnt(0)
; #define LDS_WAIT() asm volatile("s_waitcnt lgkmcnt(0)" ::: "memory")
; __device__ __forceinline__ void p2_conv_unit_prompt(Frame& F, int unit, int next_pm, const ConvW& cw, size_t src_off = WS_A, size_t dst_off = WS_CACT) {
;     ...
;         LDS_WAIT(); __syncthreads();
;         if (F.tid < 16) { float s1 = 0.f, s2 = 0.f;
; #pragma unroll
;             for (int w = 0; w < 8; ++w) { s1 += WPT[w * 32 + F.tid]; s2 += WPT[w * 32 + 16 + F.tid]; }
;             const float mean = s1 * (1.0f / DCONV), var = fmaxf(s2 * (1.0f / DCONV) - mean * mean, 0.f);
;             MR[2 * F.tid] = mean; MR[2 * F.tid + 1] = 1.0f / sqrtf(var + EPS); }
.Lcs_novm:
	s_waitcnt lgkmcnt(0)
	s_barrier
	s_and_saveexec_b64 s[42:43], s[6:7]
	s_cbranch_execz .LBB0_465
	ds_read_b32 v1, v15
	ds_read_b32 v146, v48
	ds_read_b32 v147, v49
	ds_read_b32 v148, v50
	ds_read_b32 v149, v51
	ds_read_b32 v150, v52
	ds_read_b32 v151, v53
	ds_read_b32 v152, v54
	s_waitcnt lgkmcnt(7)
	v_add_f32_e32 v1, 0, v1
	s_waitcnt lgkmcnt(6)
	v_add_f32_e32 v146, 0, v146
	s_waitcnt lgkmcnt(5)
	v_add_f32_e32 v1, v1, v147
	s_waitcnt lgkmcnt(4)
	v_add_f32_e32 v146, v146, v148
	s_waitcnt lgkmcnt(3)
	v_add_f32_e32 v1, v1, v149
	s_waitcnt lgkmcnt(2)
	v_add_f32_e32 v146, v146, v150
	s_waitcnt lgkmcnt(1)
	v_add_f32_e32 v1, v1, v151
	s_waitcnt lgkmcnt(0)
	v_add_f32_e32 v146, v146, v152
	ds_read_b32 v147, v55
	ds_read_b32 v148, v56
	ds_read_b32 v149, v57
	ds_read_b32 v150, v122
	ds_read_b32 v151, v123
	ds_read_b32 v152, v124
	ds_read_b32 v153, v125
	ds_read_b32 v154, v126
	s_waitcnt lgkmcnt(7)
	v_add_f32_e32 v1, v1, v147
	s_waitcnt lgkmcnt(6)
	v_add_f32_e32 v146, v146, v148
	s_waitcnt lgkmcnt(5)
	v_add_f32_e32 v1, v1, v149
	s_waitcnt lgkmcnt(4)
	v_add_f32_e32 v146, v146, v150
	s_waitcnt lgkmcnt(3)
	v_add_f32_e32 v1, v1, v151
	s_waitcnt lgkmcnt(2)
	v_add_f32_e32 v146, v146, v152
	s_waitcnt lgkmcnt(1)
	v_add_f32_e32 v1, v1, v153
	s_waitcnt lgkmcnt(0)
	v_add_f32_e32 v147, v146, v154
	v_mul_f32_e32 v146, 0x3a2aaaab, v1
	v_mul_f32_e32 v1, v146, v146
	v_fma_f32 v1, v147, s55, -v1
	v_max_f32_e32 v1, 0, v1
	v_add_f32_e32 v1, 0x358637bd, v1
	v_mul_f32_e32 v147, 0x4f800000, v1
	v_cmp_gt_f32_e32 vcc, s56, v1
	s_nop 1
	v_cndmask_b32_e32 v1, v1, v147, vcc
	v_sqrt_f32_e32 v147, v1
	s_nop 0
	v_add_u32_e32 v148, -1, v147
	v_fma_f32 v149, -v148, v147, v1
	v_cmp_ge_f32_e64 s[12:13], 0, v149
	v_add_u32_e32 v149, 1, v147
	s_nop 0
	v_cndmask_b32_e64 v148, v147, v148, s[12:13]
	v_fma_f32 v147, -v149, v147, v1
	v_cmp_lt_f32_e64 s[12:13], 0, v147
	s_nop 1
	v_cndmask_b32_e64 v147, v148, v149, s[12:13]
	v_mul_f32_e32 v148, 0x37800000, v147
	v_cndmask_b32_e32 v147, v147, v148, vcc
	v_cmp_class_f32_e32 vcc, v1, v128
	s_nop 1
	v_cndmask_b32_e32 v1, v147, v1, vcc
	v_div_scale_f32 v147, s[12:13], v1, v1, 1.0
	v_rcp_f32_e32 v148, v147
	s_nop 0
	v_fma_f32 v149, -v147, v148, 1.0
	v_fmac_f32_e32 v148, v149, v148
	v_div_scale_f32 v149, vcc, 1.0, v1, 1.0
	v_mul_f32_e32 v150, v149, v148
	v_fma_f32 v151, -v147, v150, v149
	v_fmac_f32_e32 v150, v151, v148
	v_fma_f32 v147, -v147, v150, v149
	v_div_fmas_f32 v147, v147, v148, v150
	v_div_fixup_f32 v147, v147, v1, 1.0
	ds_write_b64 v127, v[146:147]
	s_branch .LBB0_465
